# prologue de-serialisation: K-tile-1 staging DMAs of all 7 GEMM phase prologues hoisted above the K-tile-0 wait (one round trip instead of two)
# speedup vs baseline: 1.0068x; 1.0068x over previous
; #define PG8_LAS __attribute__((address_space(3)))
; #define PG8_STAGE(bufoff, gbase, voff) do { _Pragma("unroll") for (int _i = 0; _i < 2; ++_i) \
;         __builtin_amdgcn_global_load_lds((const unsigned*)((const char*)(gbase) + (voff)[_i]), (PG8_LAS unsigned*)(lds + (bufoff) + ldsw + _i * 8192), 16, 0, 0); } while (0)
; #define PG8_WAIT_V(n) asm volatile("s_waitcnt vmcnt(" #n ")" ::: "memory")
; #define PG8_BAR __builtin_amdgcn_s_barrier()
; template <class Epi, class Sched, bool ALIGN_EPI = false, bool SP2 = false, bool HALFM = false, bool AMAP = false>
; __device__ __forceinline__ void gemm_phase(PG8_LAS unsigned char* lds, const Gemm g, const Sched& S, const Epi& E, int tid_in) {
;     ...
;     for (int i = 0; i < 2; ++i) { int R, C; stage_rc(tid * 16 + i * 8192, R, C); const int Rb = Epi::PERM ? ((R & ~31) + perm32(R & 31)) : R;
;         const int Ra = AMAP ? (64 * ((R >> 4) & 3) + 16 * (R >> 6) + (R & 15)) : R;
;         voffA[i] = (unsigned)(Ra * g.lda + C) * 2u; voffB[i] = (unsigned)(Rb * g.ldb + C) * 2u; }
;     ...
;     const char* cA = gA + PG8_ATILE(cur.pm); const char* cB = gB + (size_t)cur.pn * tstepB;
;     S.a_ready(cur);
;     if constexpr (SP2) {
;         PG8_STAGE(PG8_SB(0, 0), cB, voffB); PG8_STAGE(PG8_SB(0, 1), cB + hstepB, voffB); PG8_STAGE(PG8_SA(0, 0), cA, voffA); if constexpr (!HALFM) PG8_STAGE(PG8_SA(0, 1), cA + hstepA, voffA);
;         if constexpr (Epi::RSTD) E.prime((PG8_LAS float*)(lds + STAGE_BYTES), cur, tid);
;         if (wr == 1) PG8_BAR;
;         if constexpr (HALFM) PG8_WAIT_V(0); else PG8_WAIT_V(2);
;         PG8_BAR;
;         PG8_STAGE(PG8_SB(1, 0), cB + kstep, voffB); PG8_STAGE(PG8_SA(1, 0), cA + kstep, voffA); PG8_STAGE(PG8_SB(1, 1), cB + hstepB + kstep, voffB);
.LBB0_152:
	s_mov_b64 s[6:7], s[0:1]
	s_load_dwordx2 s[16:17], s[6:7], 0xa8
	v_readlane_b32 s5, v255, 46
	v_mbcnt_lo_u32_b32 v0, -1, 0
	v_mbcnt_hi_u32_b32 v0, -1, v0
	s_waitcnt lgkmcnt(0)
	s_add_u32 s8, s16, 0x1000000
	s_addc_u32 s9, s17, 0
	s_or_b32 s88, s4, s5
	s_mul_i32 s19, s88, 0x2c00000
	s_mul_hi_u32 s18, s88, 0x2c00000
	s_add_u32 s4, s16, s19
	s_addc_u32 s5, s17, s18
	s_add_u32 s12, s4, 0x14800000
	s_addc_u32 s13, s5, 0
	v_readlane_b32 s4, v255, 31
	v_or_b32_e32 v8, s92, v0
	v_readlane_b32 s5, v255, 32
	s_andn2_b64 vcc, exec, s[4:5]
	v_readfirstlane_b32 s20, v8
	s_cbranch_vccnz .LBB0_174
	v_lshlrev_b32_e32 v0, 4, v8
	v_add_u32_e32 v1, 0x2000, v0
	v_ashrrev_i32_e32 v2, 31, v1
	v_lshrrev_b32_e32 v2, 22, v2
	v_add_u32_e32 v2, v1, v2
	v_ashrrev_i32_e32 v9, 10, v2
	v_mul_i32_i24_e32 v2, 0x400, v9
	v_sub_u32_e32 v1, v1, v2
	v_lshrrev_b32_e32 v2, 4, v1
	v_bitop3_b32 v1, v2, v1, 32 bitop3:0x6c
	v_ashrrev_i32_e32 v2, 31, v1
	v_lshrrev_b32_e32 v2, 26, v2
	v_add_u32_e32 v2, v1, v2
	v_lshlrev_b32_e32 v3, 3, v9
	v_ashrrev_i32_e32 v10, 6, v2
	v_and_b32_e32 v3, -16, v3
	v_add_u32_e32 v3, v10, v3
	v_and_b32_e32 v4, 3, v10
	s_mov_b32 s4, 0xfffe0
	v_lshrrev_b32_e32 v5, 2, v3
	v_lshlrev_b32_e32 v6, 1, v3
	v_and_b32_e32 v2, 0xc0, v2
	v_and_or_b32 v4, v3, s4, v4
	v_and_b32_e32 v5, 4, v5
	v_and_b32_e32 v6, 24, v6
	v_sub_u32_e32 v1, v1, v2
	v_or3_b32 v4, v4, v5, v6
	v_lshlrev_b32_e32 v5, 5, v9
	v_ashrrev_i16_sdwa v1, v254, sext(v1) dst_sel:DWORD dst_unused:UNUSED_PAD src0_sel:DWORD src1_sel:BYTE_0
	v_and_b32_e32 v5, 32, v5
	v_bfe_i32 v11, v1, 0, 16
	v_add_lshl_u32 v1, v5, v11, 1
	v_lshl_add_u32 v172, v4, 12, v1
	v_lshl_add_u32 v174, v3, 12, v1
	v_bfe_i32 v1, v8, 27, 1
	v_lshrrev_b32_e32 v1, 22, v1
	v_add_u32_e32 v1, v0, v1
	v_and_b32_e32 v1, 0xfffffc00, v1
	v_sub_u32_e32 v0, v0, v1
	v_lshrrev_b32_e32 v1, 4, v0
	v_ashrrev_i32_e32 v2, 31, v8
	v_bitop3_b32 v0, v1, v0, 32 bitop3:0x6c
	v_lshrrev_b32_e32 v2, 26, v2
	v_ashrrev_i32_e32 v1, 31, v0
	v_add_u32_e32 v2, v8, v2
	v_lshrrev_b32_e32 v1, 26, v1
	v_ashrrev_i32_e32 v13, 6, v2
	v_add_u32_e32 v1, v0, v1
	v_lshlrev_b32_e32 v2, 3, v13
	v_ashrrev_i32_e32 v12, 6, v1
	v_and_b32_e32 v2, -16, v2
	v_add_u32_e32 v2, v12, v2
	v_and_b32_e32 v3, 3, v12
	v_lshrrev_b32_e32 v4, 2, v2
	v_lshlrev_b32_e32 v5, 1, v2
	v_and_b32_e32 v1, 0xc0, v1
	v_and_or_b32 v3, v2, s4, v3
	v_and_b32_e32 v4, 4, v4
	v_and_b32_e32 v5, 24, v5
	v_sub_u32_e32 v0, v0, v1
	v_or3_b32 v3, v3, v4, v5
	v_lshlrev_b32_e32 v4, 5, v13
	v_ashrrev_i16_sdwa v0, v254, sext(v0) dst_sel:DWORD dst_unused:UNUSED_PAD src0_sel:DWORD src1_sel:BYTE_0
	s_add_u32 s22, s16, 0x300000
	v_and_b32_e32 v4, 32, v4
	v_bfe_i32 v14, v0, 0, 16
	v_readlane_b32 s4, v255, 10
	s_addc_u32 s23, s17, 0
	s_ashr_i32 s21, s20, 6
	v_add_lshl_u32 v0, v4, v14, 1
	v_readlane_b32 s5, v255, 11
	s_lshl_b32 s10, s21, 10
	v_lshl_add_u32 v176, v3, 12, v0
	v_lshl_add_u32 v184, v2, 12, v0
	v_mov_b64_e32 v[0:1], s[4:5]
	v_lshl_add_u64 v[16:17], s[12:13], 0, v[0:1]
	s_add_i32 s11, s10, 0
	s_add_i32 m0, s11, 0x10000
	v_lshl_add_u64 v[0:1], v[16:17], 0, v[176:177]
	v_mov_b32_e32 v173, v177
	s_mov_b64 s[6:7], 0x80000
	global_load_lds_dwordx4 v[0:1], off
	v_lshl_add_u64 v[2:3], v[16:17], 0, v[172:173]
	s_add_i32 m0, s11, 0x12000
	v_lshl_add_u64 v[4:5], v[16:17], 0, s[6:7]
	global_load_lds_dwordx4 v[2:3], off
	s_add_i32 m0, s11, 0x14000
	v_lshl_add_u64 v[6:7], v[4:5], 0, v[176:177]
	v_readlane_b32 s4, v255, 8
	global_load_lds_dwordx4 v[6:7], off
	v_lshl_add_u64 v[4:5], v[4:5], 0, v[172:173]
	s_add_i32 m0, s11, 0x16000
	v_readlane_b32 s5, v255, 9
	global_load_lds_dwordx4 v[4:5], off
	s_nop 0
	v_mov_b64_e32 v[4:5], s[4:5]
	v_lshl_add_u64 v[18:19], s[8:9], 0, v[4:5]
	v_mov_b32_e32 v185, v177
	v_lshl_add_u64 v[4:5], v[18:19], 0, v[184:185]
	s_mov_b32 m0, s11
	v_mov_b32_e32 v175, v177
	s_add_i32 s25, s11, 0x2000
	global_load_lds_dwordx4 v[4:5], off
	v_lshl_add_u64 v[6:7], v[18:19], 0, v[174:175]
	s_mov_b32 m0, s25
	v_lshl_add_u64 v[20:21], v[18:19], 0, s[6:7]
	s_add_i32 s36, s11, 0x4000
	global_load_lds_dwordx4 v[6:7], off
	v_lshl_add_u64 v[22:23], v[20:21], 0, v[184:185]
	s_mov_b32 m0, s36
	s_add_i32 s37, s11, 0x6000
	global_load_lds_dwordx4 v[22:23], off
	v_lshl_add_u64 v[20:21], v[20:21], 0, v[174:175]
	s_mov_b32 m0, s37
	v_readfirstlane_b32 s28, v16
	global_load_lds_dwordx4 v[20:21], off
	v_readfirstlane_b32 s29, v17
	s_add_i32 m0, s11, 0x18000
	v_lshl_add_u64 v[0:1], v[0:1], 0, s[66:67]
	global_load_lds_dwordx4 v[0:1], off
	v_lshl_add_u64 v[0:1], v[2:3], 0, s[66:67]
	s_add_i32 m0, s11, 0x1a000
	s_add_i32 s38, s11, 0x8000
	s_add_i32 s39, s11, 0xa000
	global_load_lds_dwordx4 v[0:1], off
	v_lshl_add_u64 v[0:1], v[4:5], 0, s[66:67]
	s_mov_b32 m0, s38
	s_add_u32 s30, s28, 0x80080
	global_load_lds_dwordx4 v[0:1], off
	v_lshl_add_u64 v[0:1], v[6:7], 0, s[66:67]
	s_mov_b32 m0, s39
	s_addc_u32 s31, s29, 0
	global_load_lds_dwordx4 v[0:1], off
	s_add_i32 m0, s11, 0x1c000
	v_lshl_add_u64 v[0:1], s[30:31], 0, v[176:177]
	global_load_lds_dwordx4 v[0:1], off
	v_lshl_add_u64 v[0:1], s[30:31], 0, v[172:173]
	s_add_i32 m0, s11, 0x1e000
	s_nop 0
	global_load_lds_dwordx4 v[0:1], off
	v_readfirstlane_b32 s6, v18
	v_readfirstlane_b32 s7, v19
	v_cmp_gt_i32_e32 vcc, s89, v8
	s_and_saveexec_b64 s[14:15], vcc
	s_cbranch_execz .LBB0_155
; #define PG8_LAS __attribute__((address_space(3)))
; __device__ __forceinline__ float row_rstd(const float* ssq, int row) {
;     const f32x4* p = (const f32x4*)(ssq + (size_t)row * 32); f32x4 v[8];
; #pragma unroll
;     for (int i = 0; i < 8; ++i) v[i] = p[i];
;     float s = 0.f;
; #pragma unroll
;     for (int i = 0; i < 8; ++i) s += (v[i][0] + v[i][1]) + (v[i][2] + v[i][3]);
;     return 1.0f / sqrtf(s * (1.0f / 2048.0f) + 1e-6f);
; }
;     __device__ __forceinline__ void prime(PG8_LAS float* rc, const Unit& u, int tid) const {
;         if (tid < (HALFM ? HALF : BM)) rc[tid] = row_rstd(ssq, u.pm * (HALFM ? HALF : BM) + tid);
;         asm volatile("s_waitcnt lgkmcnt(0)" ::: "memory");
	v_readlane_b32 s4, v255, 12
	s_nop 1
	v_add_u32_e32 v16, s4, v8
	v_ashrrev_i32_e32 v17, 31, v16
	v_lshlrev_b64 v[16:17], 7, v[16:17]
	v_lshl_add_u64 v[44:45], s[22:23], 0, v[16:17]
	global_load_dwordx4 v[16:19], v[44:45], off
	global_load_dwordx4 v[20:23], v[44:45], off offset:16
	global_load_dwordx4 v[24:27], v[44:45], off offset:32
	global_load_dwordx4 v[28:31], v[44:45], off offset:48
	global_load_dwordx4 v[32:35], v[44:45], off offset:64
	global_load_dwordx4 v[36:39], v[44:45], off offset:80
	global_load_dwordx4 v[40:43], v[44:45], off offset:96
	s_nop 0
	global_load_dwordx4 v[44:47], v[44:45], off offset:112
	s_waitcnt vmcnt(0)
	v_mov_b32_e32 v48, v16
	v_mov_b32_e32 v49, v20
	v_mov_b32_e32 v20, v17
	v_mov_b32_e32 v16, v18
	v_mov_b32_e32 v17, v22
	v_mov_b32_e32 v22, v19
	v_mov_b32_e32 v18, v25
	v_mov_b32_e32 v19, v26
	v_mov_b32_e32 v25, v27
	v_pk_add_f32 v[20:21], v[48:49], v[20:21]
	v_pk_add_f32 v[16:17], v[16:17], v[22:23]
	v_pk_add_f32 v[18:19], v[18:19], v[24:25]
	v_pk_add_f32 v[16:17], v[20:21], v[16:17]
	v_pk_add_f32 v[18:19], v[18:19], v[18:19] op_sel:[0,1] op_sel_hi:[1,0]
	v_add_f32_e32 v15, 0, v16
	v_add_f32_e32 v26, v28, v29
	v_add_f32_e32 v28, v30, v31
	v_mov_b32_e32 v31, v32
	v_mov_b32_e32 v27, v34
	v_mov_b32_e32 v29, v35
	v_mov_b32_e32 v19, v33
	v_add_f32_e32 v30, v15, v17
	v_mov_b32_e32 v34, v37
	v_mov_b32_e32 v35, v38
	v_mov_b32_e32 v37, v39
	v_pk_add_f32 v[22:23], v[26:27], v[28:29]
	v_pk_add_f32 v[16:17], v[30:31], v[18:19]
	v_pk_add_f32 v[24:25], v[34:35], v[36:37]
	v_pk_add_f32 v[16:17], v[16:17], v[22:23]
	v_pk_add_f32 v[20:21], v[24:25], v[24:25] op_sel:[0,1] op_sel_hi:[1,0]
	v_pk_add_f32 v[16:17], v[16:17], v[16:17] op_sel:[0,1] op_sel_hi:[1,0]
	v_add_f32_e32 v38, v40, v41
	v_add_f32_e32 v40, v42, v43
	v_mov_b32_e32 v39, v46
	v_mov_b32_e32 v41, v47
	v_mov_b32_e32 v21, v45
	v_mov_b32_e32 v17, v44
	v_pk_add_f32 v[26:27], v[38:39], v[40:41]
	v_pk_add_f32 v[16:17], v[16:17], v[20:21]
	s_nop 0
	v_pk_add_f32 v[16:17], v[16:17], v[26:27]
	s_nop 0
	v_add_f32_e32 v15, v16, v17
	v_fmamk_f32 v15, v15, 0x3a000000, v221
	v_mul_f32_e32 v16, 0x4f800000, v15
	v_cmp_gt_f32_e32 vcc, s52, v15
	s_nop 1
	v_cndmask_b32_e32 v15, v15, v16, vcc
	v_sqrt_f32_e32 v16, v15
	s_nop 0
	v_add_u32_e32 v17, -1, v16
	v_add_u32_e32 v18, 1, v16
	v_fma_f32 v19, -v17, v16, v15
	v_fma_f32 v20, -v18, v16, v15
	v_cmp_ge_f32_e64 s[4:5], 0, v19
	s_nop 1
	v_cndmask_b32_e64 v16, v16, v17, s[4:5]
	v_cmp_lt_f32_e64 s[4:5], 0, v20
	s_nop 1
	v_cndmask_b32_e64 v16, v16, v18, s[4:5]
	v_mul_f32_e32 v17, 0x37800000, v16
	v_cndmask_b32_e32 v16, v16, v17, vcc
	v_cmp_class_f32_e32 vcc, v15, v226
	v_lshl_add_u32 v18, v8, 2, 0
	s_nop 0
	v_cndmask_b32_e32 v15, v16, v15, vcc
	v_div_scale_f32 v16, s[4:5], v15, v15, 1.0
	v_rcp_f32_e32 v17, v16
	v_div_scale_f32 v19, vcc, 1.0, v15, 1.0
	v_fma_f32 v20, -v16, v17, 1.0
	v_fmac_f32_e32 v17, v20, v17
	v_mul_f32_e32 v20, v19, v17
	v_fma_f32 v21, -v16, v20, v19
	v_fmac_f32_e32 v20, v21, v17
	v_fma_f32 v16, -v16, v20, v19
	v_div_fmas_f32 v16, v16, v17, v20
	v_div_fixup_f32 v15, v16, v15, 1.0
	v_add_u32_e32 v16, 0x20000, v18
	ds_write_b32 v16, v15

; #define PG8_STAGE(bufoff, gbase, voff) do { _Pragma("unroll") for (int _i = 0; _i < 2; ++_i) \
;         __builtin_amdgcn_global_load_lds((const unsigned*)((const char*)(gbase) + (voff)[_i]), (PG8_LAS unsigned*)(lds + (bufoff) + ldsw + _i * 8192), 16, 0, 0); } while (0)
; #define PG8_WAIT_V(n) asm volatile("s_waitcnt vmcnt(" #n ")" ::: "memory")
; #define PG8_BAR __builtin_amdgcn_s_barrier()
; template <class Epi, class Sched, bool ALIGN_EPI = false, bool SP2 = false, bool HALFM = false, bool AMAP = false>
; __device__ __forceinline__ void gemm_phase(PG8_LAS unsigned char* lds, const Gemm g, const Sched& S, const Epi& E, int tid_in) {
;     ...
;     const unsigned ldsw = (unsigned)wid * 1024u;
;     const int aoff = lds_byte(wr * 64 + fr, fq * 8), boff = lds_byte(wc * 32 + fr, fq * 8);
;     ...
;         if (wr == 1) PG8_BAR;
;         if constexpr (HALFM) PG8_WAIT_V(0); else PG8_WAIT_V(2);
;         PG8_BAR;
;         PG8_STAGE(PG8_SB(1, 0), cB + kstep, voffB); PG8_STAGE(PG8_SA(1, 0), cA + kstep, voffA); PG8_STAGE(PG8_SB(1, 1), cB + hstepB + kstep, voffB);
;         PG8_WAIT_V(6); PG8_BAR;
.LBB0_157:
	s_add_u32 s16, s16, 0x3000000
	s_addc_u32 s17, s17, 0
	s_lshl_b32 s21, s21, 5
	s_and_b32 s42, s21, 0x60
	s_lshl_b32 s5, s4, 13
	s_lshl_b32 s21, s42, 7
	s_waitcnt vmcnt(2)
	s_barrier
	s_cmpk_lt_u32 s20, 0x100
	v_lshrrev_b32_e32 v1, 1, v8
	v_and_b32_e32 v0, 15, v8
	v_and_b32_e32 v2, 24, v1
	v_lshlrev_b32_e32 v1, 1, v2
	v_lshlrev_b32_e32 v3, 2, v0
	v_lshl_or_b32 v204, s4, 6, v0
	v_lshl_or_b32 v1, v0, 6, v1
	v_and_b32_e32 v0, 32, v3
	v_bitop3_b32 v4, v1, s5, v0 bitop3:0xde
	v_bitop3_b32 v205, v1, s21, v0 bitop3:0xde
	v_lshlrev_b32_e32 v0, 2, v2
	v_mov_b32_e32 v1, v177
	v_lshl_add_u64 v[186:187], s[22:23], 0, v[0:1]
	v_lshlrev_b32_e32 v0, 15, v9
	v_and_b32_e32 v0, 0xffff0000, v0
	v_lshl_add_u32 v0, v10, 12, v0
	v_and_b32_e32 v1, 1, v9
	v_lshl_or_b32 v0, v1, 6, v0
	v_lshl_add_u32 v188, v11, 1, v0
	v_lshlrev_b32_e32 v0, 15, v13
	s_cselect_b64 s[20:21], -1, 0
	s_lshl_b32 s4, s4, 8
	v_and_b32_e32 v0, 0xffff0000, v0
	s_waitcnt vmcnt(6)
	s_add_i32 s4, s4, 0
	v_lshl_add_u32 v0, v12, 12, v0
	v_and_b32_e32 v1, 1, v13
	s_add_i32 s4, s4, 0x20000
	v_lshl_or_b32 v0, v1, 6, v0
	v_add_u32_e32 v206, s4, v3
	v_or_b32_e32 v207, s42, v2
	v_mov_b32_e32 v189, v177
	v_lshl_add_u32 v190, v14, 1, v0
	v_mov_b32_e32 v191, v177
	s_mov_b32 s48, 0
	v_add_u32_e32 v208, 0, v4
	v_readlane_b32 s49, v255, 7
	s_mov_b32 s58, s26
	s_barrier
	s_branch .LBB0_160

; #define PG8_LAS __attribute__((address_space(3)))
;     __host__ __device__ bool next(int i, Unit& u) const { return i == 0 && S.next(r, u); }
; #define PG8_STAGE(bufoff, gbase, voff) do { _Pragma("unroll") for (int _i = 0; _i < 2; ++_i) \
;         __builtin_amdgcn_global_load_lds((const unsigned*)((const char*)(gbase) + (voff)[_i]), (PG8_LAS unsigned*)(lds + (bufoff) + ldsw + _i * 8192), 16, 0, 0); } while (0)
; #define PG8_WAIT_V(n) asm volatile("s_waitcnt vmcnt(" #n ")" ::: "memory")
; #define PG8_BAR __builtin_amdgcn_s_barrier()
;     __host__ __device__ void unit_of(int L, Unit& u) const {
;         int wgid = L; { const int q = nwg / NXCD, r = nwg % NXCD, xcd = wgid % NXCD, off = wgid / NXCD; wgid = (xcd < r ? xcd * (q + 1) : r * (q + 1) + (xcd - r) * q) + off; }
;         const int nig = wgm * nN, gid = wgid / nig, fm = gid * wgm, gsz = (nM - fm) < wgm ? (nM - fm) : wgm;
;         u.pm = fm + ((wgid % nig) % gsz); u.pn = (wgid % nig) / gsz;
;         if (nwg == NXCD * nig && nwg % NXCD == 0) u.pn = (u.pn + (L % NXCD) * (nN / NXCD)) % nN;
;     }
;     __host__ __device__ bool next(int i, Unit& u) const {
;         const long L = (long)i * G + c; if (L >= nlim) return false;
;         unit_of((int)L, u); return true;
;     }
;         S.unit_of(first + (int)(j % ntail), u); u.pm = 2 * u.pm + (int)(j / ntail); return true; }
; template <class Epi, class Sched, bool ALIGN_EPI = false, bool SP2 = false, bool HALFM = false, bool AMAP = false>
; __device__ __forceinline__ void gemm_phase(PG8_LAS unsigned char* lds, const Gemm g, const Sched& S, const Epi& E, int tid_in) {
;     ...
;     const char* cA = gA + PG8_ATILE(cur.pm); const char* cB = gB + (size_t)cur.pn * tstepB;
;     S.a_ready(cur);
;     if constexpr (SP2) {
;         PG8_STAGE(PG8_SB(0, 0), cB, voffB); PG8_STAGE(PG8_SB(0, 1), cB + hstepB, voffB); PG8_STAGE(PG8_SA(0, 0), cA, voffA); if constexpr (!HALFM) PG8_STAGE(PG8_SA(0, 1), cA + hstepA, voffA);
;         if constexpr (Epi::RSTD) E.prime((PG8_LAS float*)(lds + STAGE_BYTES), cur, tid);
;         if (wr == 1) PG8_BAR;
;         if constexpr (HALFM) PG8_WAIT_V(0); else PG8_WAIT_V(2);
;         PG8_BAR;
;         PG8_STAGE(PG8_SB(1, 0), cB + kstep, voffB); PG8_STAGE(PG8_SA(1, 0), cA + kstep, voffA); PG8_STAGE(PG8_SB(1, 1), cB + hstepB + kstep, voffB);
.LBB0_178:
	v_lshlrev_b32_e32 v0, 4, v10
	v_add_u32_e32 v1, 0x2000, v0
	v_ashrrev_i32_e32 v2, 31, v1
	v_lshrrev_b32_e32 v2, 22, v2
	v_add_u32_e32 v2, v1, v2
	v_ashrrev_i32_e32 v2, 10, v2
	v_mul_i32_i24_e32 v3, 0x400, v2
	v_sub_u32_e32 v1, v1, v3
	v_lshrrev_b32_e32 v3, 4, v1
	v_bitop3_b32 v1, v3, v1, 32 bitop3:0x6c
	v_ashrrev_i32_e32 v3, 31, v1
	v_lshrrev_b32_e32 v3, 26, v3
	v_add_u32_e32 v3, v1, v3
	v_lshlrev_b32_e32 v5, 3, v2
	v_ashrrev_i32_e32 v4, 6, v3
	v_and_b32_e32 v5, -16, v5
	v_and_b32_e32 v3, 0xc0, v3
	v_add_u32_e32 v5, v4, v5
	v_sub_u32_e32 v1, v1, v3
	v_and_b32_e32 v4, 3, v4
	s_mov_b32 s5, 0xfffe0
	v_lshrrev_b32_e32 v6, 2, v5
	v_lshlrev_b32_e32 v7, 1, v5
	v_lshlrev_b32_e32 v2, 5, v2
	v_ashrrev_i16_sdwa v1, v254, sext(v1) dst_sel:DWORD dst_unused:UNUSED_PAD src0_sel:DWORD src1_sel:BYTE_0
	v_and_or_b32 v4, v5, s5, v4
	v_and_b32_e32 v6, 4, v6
	v_and_b32_e32 v7, 24, v7
	v_and_b32_e32 v2, 32, v2
	v_bfe_i32 v1, v1, 0, 16
	v_or3_b32 v4, v4, v6, v7
	v_add_lshl_u32 v1, v2, v1, 1
	v_lshl_add_u32 v108, v4, 12, v1
	v_lshl_add_u32 v110, v5, 12, v1
	v_bfe_i32 v1, v10, 27, 1
	v_lshrrev_b32_e32 v1, 22, v1
	v_add_u32_e32 v1, v0, v1
	v_and_b32_e32 v1, 0xfffffc00, v1
	v_sub_u32_e32 v0, v0, v1
	v_lshrrev_b32_e32 v1, 4, v0
	v_ashrrev_i32_e32 v3, 31, v10
	v_bitop3_b32 v0, v1, v0, 32 bitop3:0x6c
	v_lshrrev_b32_e32 v3, 26, v3
	v_ashrrev_i32_e32 v1, 31, v0
	v_add_u32_e32 v3, v10, v3
	v_lshrrev_b32_e32 v1, 26, v1
	v_ashrrev_i32_e32 v3, 6, v3
	v_add_u32_e32 v1, v0, v1
	v_lshlrev_b32_e32 v4, 3, v3
	v_ashrrev_i32_e32 v2, 6, v1
	v_and_b32_e32 v4, -16, v4
	v_add_u32_e32 v4, v2, v4
	v_and_b32_e32 v2, 3, v2
	v_and_or_b32 v2, v4, s5, v2
	s_add_u32 s28, s20, 0x300000
	s_mul_i32 s5, s4, s27
	s_addc_u32 s29, s21, 0
	s_sub_i32 s5, s2, s5
	s_add_i32 s5, s50, s5
	s_ashr_i32 s6, s5, 31
	s_lshr_b32 s6, s6, 29
	s_add_i32 s6, s5, s6
	s_ashr_i32 s18, s23, 6
	s_ashr_i32 s7, s6, 3
	s_and_b32 s6, s6, -8
	s_lshl_b32 s10, s18, 10
	s_sub_i32 s5, s5, s6
	s_cmp_lt_i32 s5, 0
	s_cselect_b32 s6, s34, 0xb0
	s_mul_i32 s6, s5, s6
	s_add_i32 s6, s6, s7
	s_mul_hi_i32 s7, s6, 0x2e8ba2e9
	s_lshr_b32 s11, s7, 31
	s_ashr_i32 s7, s7, 5
	v_and_b32_e32 v1, 0xc0, v1
	s_add_i32 s7, s7, s11
	v_sub_u32_e32 v0, v0, v1
	s_lshl_b32 s11, s7, 2
	v_lshrrev_b32_e32 v5, 2, v4
	v_lshlrev_b32_e32 v6, 1, v4
	v_lshlrev_b32_e32 v3, 5, v3
	v_ashrrev_i16_sdwa v0, v254, sext(v0) dst_sel:DWORD dst_unused:UNUSED_PAD src0_sel:DWORD src1_sel:BYTE_0
	s_sub_i32 s14, 32, s11
	v_and_b32_e32 v5, 4, v5
	v_and_b32_e32 v6, 24, v6
	v_and_b32_e32 v3, 32, v3
	v_bfe_i32 v0, v0, 0, 16
	s_min_i32 s14, s14, 4
	v_or3_b32 v2, v2, v5, v6
	v_add_lshl_u32 v0, v3, v0, 1
	s_abs_i32 s16, s14
	v_lshl_add_u32 v176, v2, 12, v0
	v_lshl_add_u32 v112, v4, 12, v0
	v_cvt_f32_u32_e32 v0, s16
	s_sub_i32 s17, 0, s16
	s_mulk_i32 s7, 0xb0
	s_sub_i32 s6, s6, s7
	v_rcp_iflag_f32_e32 v0, v0
	s_abs_i32 s15, s6
	s_xor_b32 s7, s6, s14
	s_ashr_i32 s7, s7, 31
	v_mul_f32_e32 v0, 0x4f7ffffe, v0
	v_cvt_u32_f32_e32 v0, v0
	s_mul_i32 s5, s5, 5
	v_mov_b32_e32 v109, v177
	v_mov_b32_e32 v113, v177
	v_readfirstlane_b32 s19, v0
	s_mul_i32 s17, s17, s19
	s_mul_hi_u32 s17, s19, s17
	s_add_i32 s19, s19, s17
	s_mul_hi_u32 s17, s15, s19
	s_mul_i32 s19, s17, s16
	s_sub_i32 s15, s15, s19
	s_add_i32 s19, s17, 1
	s_sub_i32 s22, s15, s16
	s_cmp_ge_u32 s15, s16
	s_cselect_b32 s17, s19, s17
	s_cselect_b32 s15, s22, s15
	s_add_i32 s19, s17, 1
	s_cmp_ge_u32 s15, s16
	s_cselect_b32 s15, s19, s17
	s_xor_b32 s15, s15, s7
	s_sub_i32 s7, s15, s7
	s_mul_i32 s14, s7, s14
	s_sub_i32 s6, s6, s14
	s_add_i32 s5, s7, s5
	s_add_i32 s11, s11, s6
	s_mul_i32 s6, s5, 0xba3
	s_lshr_b32 s7, s6, 31
	s_lshr_b32 s6, s6, 17
	s_add_i32 s6, s6, s7
	s_mul_i32 s6, s6, 44
	s_sub_i32 s22, s5, s6
	s_bfe_i64 s[6:7], s[22:23], 0x100000
	s_lshl_b64 s[6:7], s[6:7], 20
	v_mov_b64_e32 v[0:1], s[6:7]
	s_lshl_b32 s5, s11, 1
	v_lshl_add_u64 v[0:1], s[12:13], 0, v[0:1]
	s_add_i32 s11, s10, 0
	s_add_i32 m0, s11, 0x10000
	v_lshl_add_u64 v[2:3], v[0:1], 0, v[176:177]
	s_mov_b64 s[16:17], 0x80000
	s_add_i32 s14, s5, s4
	v_readfirstlane_b32 s6, v0
	v_readfirstlane_b32 s7, v1
	global_load_lds_dwordx4 v[2:3], off
	v_lshl_add_u64 v[4:5], v[0:1], 0, v[108:109]
	s_add_i32 m0, s11, 0x12000
	v_lshl_add_u64 v[0:1], v[0:1], 0, s[16:17]
	s_ashr_i32 s15, s14, 31
	global_load_lds_dwordx4 v[4:5], off
	s_add_i32 m0, s11, 0x14000
	v_lshl_add_u64 v[6:7], v[0:1], 0, v[176:177]
	s_lshl_b64 s[4:5], s[14:15], 19
	global_load_lds_dwordx4 v[6:7], off
	v_lshl_add_u64 v[0:1], v[0:1], 0, v[108:109]
	s_add_i32 m0, s11, 0x16000
	v_mov_b32_e32 v111, v177
	global_load_lds_dwordx4 v[0:1], off
	v_mov_b64_e32 v[0:1], s[4:5]
	v_lshl_add_u64 v[0:1], s[8:9], 0, v[0:1]
	v_lshl_add_u64 v[6:7], v[0:1], 0, v[112:113]
	s_mov_b32 m0, s11
	s_add_i32 s15, s11, 0x2000
	global_load_lds_dwordx4 v[6:7], off
	v_lshl_add_u64 v[8:9], v[0:1], 0, v[110:111]
	s_mov_b32 m0, s15
	s_movk_i32 s4, 0x80
	global_load_lds_dwordx4 v[8:9], off
	s_add_i32 m0, s11, 0x18000
	v_lshl_add_u64 v[2:3], v[2:3], 0, s[66:67]
	global_load_lds_dwordx4 v[2:3], off
	v_lshl_add_u64 v[2:3], v[4:5], 0, s[66:67]
	s_add_i32 m0, s11, 0x1a000
	s_add_i32 s98, s11, 0x8000
	s_add_i32 s19, s11, 0xa000
	global_load_lds_dwordx4 v[2:3], off
	v_lshl_add_u64 v[2:3], v[6:7], 0, s[66:67]
	s_mov_b32 m0, s98
	s_add_u32 s30, s6, 0x80080
	global_load_lds_dwordx4 v[2:3], off
	v_lshl_add_u64 v[2:3], v[8:9], 0, s[66:67]
	s_mov_b32 m0, s19
	s_addc_u32 s31, s7, 0
	global_load_lds_dwordx4 v[2:3], off
	s_add_i32 m0, s11, 0x1c000
	v_lshl_add_u64 v[2:3], s[30:31], 0, v[176:177]
	global_load_lds_dwordx4 v[2:3], off
	v_lshl_add_u64 v[2:3], s[30:31], 0, v[108:109]
	s_add_i32 m0, s11, 0x1e000
	s_nop 0
	global_load_lds_dwordx4 v[2:3], off
	v_cmp_gt_i32_e32 vcc, s4, v10
	s_and_saveexec_b64 s[16:17], vcc
	s_cbranch_execz .LBB0_180
; #define PG8_LAS __attribute__((address_space(3)))
; __device__ __forceinline__ float row_rstd(const float* ssq, int row) {
;     const f32x4* p = (const f32x4*)(ssq + (size_t)row * 32); f32x4 v[8];
; #pragma unroll
;     for (int i = 0; i < 8; ++i) v[i] = p[i];
;     float s = 0.f;
; #pragma unroll
;     for (int i = 0; i < 8; ++i) s += (v[i][0] + v[i][1]) + (v[i][2] + v[i][3]);
;     return 1.0f / sqrtf(s * (1.0f / 2048.0f) + 1e-6f);
; }
;     __device__ __forceinline__ void prime(PG8_LAS float* rc, const Unit& u, int tid) const {
;         if (tid < (HALFM ? HALF : BM)) rc[tid] = row_rstd(ssq, u.pm * (HALFM ? HALF : BM) + tid);
;         asm volatile("s_waitcnt lgkmcnt(0)" ::: "memory");
	v_lshl_add_u32 v12, s14, 7, v10
	v_ashrrev_i32_e32 v13, 31, v12
	v_lshlrev_b64 v[12:13], 7, v[12:13]
	v_lshl_add_u64 v[40:41], s[28:29], 0, v[12:13]
	global_load_dwordx4 v[12:15], v[40:41], off offset:48
	global_load_dwordx4 v[16:19], v[40:41], off offset:32
	global_load_dwordx4 v[20:23], v[40:41], off
	global_load_dwordx4 v[24:27], v[40:41], off offset:16
	global_load_dwordx4 v[28:31], v[40:41], off offset:112
	global_load_dwordx4 v[32:35], v[40:41], off offset:96
	global_load_dwordx4 v[36:39], v[40:41], off offset:80
	s_nop 0
	global_load_dwordx4 v[40:43], v[40:41], off offset:64
	s_waitcnt vmcnt(0)
	v_add_f32_e32 v12, v12, v13
	v_add_f32_e32 v14, v14, v15
	v_mov_b32_e32 v44, v20
	v_mov_b32_e32 v45, v24
	v_mov_b32_e32 v24, v21
	v_pk_add_f32 v[20:21], v[44:45], v[24:25]
	v_mov_b32_e32 v24, v22
	v_mov_b32_e32 v25, v26
	v_mov_b32_e32 v26, v23
	v_pk_add_f32 v[22:23], v[24:25], v[26:27]
	v_mov_b32_e32 v13, v42
	v_pk_add_f32 v[20:21], v[20:21], v[22:23]
	v_mov_b32_e32 v22, v17
	v_mov_b32_e32 v23, v18
	v_mov_b32_e32 v17, v19
	v_pk_add_f32 v[16:17], v[22:23], v[16:17]
	v_add_f32_e32 v11, 0, v20
	v_pk_add_f32 v[16:17], v[16:17], v[16:17] op_sel:[0,1] op_sel_hi:[1,0]
	v_add_f32_e32 v20, v11, v21
	v_mov_b32_e32 v21, v40
	v_mov_b32_e32 v17, v41
	v_mov_b32_e32 v15, v43
	v_pk_add_f32 v[16:17], v[20:21], v[16:17]
	v_pk_add_f32 v[12:13], v[12:13], v[14:15]
	v_mov_b32_e32 v14, v37
	v_mov_b32_e32 v15, v38
	v_mov_b32_e32 v37, v39
	v_pk_add_f32 v[12:13], v[16:17], v[12:13]
	v_pk_add_f32 v[14:15], v[14:15], v[36:37]
	v_pk_add_f32 v[12:13], v[12:13], v[12:13] op_sel:[0,1] op_sel_hi:[1,0]
	v_pk_add_f32 v[14:15], v[14:15], v[14:15] op_sel:[0,1] op_sel_hi:[1,0]
	v_add_f32_e32 v16, v32, v33
	v_add_f32_e32 v18, v34, v35
	v_mov_b32_e32 v13, v28
	v_mov_b32_e32 v15, v29
	v_mov_b32_e32 v17, v30
	v_mov_b32_e32 v19, v31
	v_pk_add_f32 v[12:13], v[12:13], v[14:15]
	v_pk_add_f32 v[14:15], v[16:17], v[18:19]
	s_nop 0
	v_pk_add_f32 v[12:13], v[12:13], v[14:15]
	s_nop 0
	v_add_f32_e32 v11, v12, v13
	v_fmamk_f32 v11, v11, 0x3a000000, v221
	v_cmp_gt_f32_e32 vcc, s52, v11
	v_mul_f32_e32 v12, 0x4f800000, v11
	s_nop 0
	v_cndmask_b32_e32 v11, v11, v12, vcc
	v_sqrt_f32_e32 v12, v11
	s_nop 0
	v_add_u32_e32 v13, -1, v12
	v_fma_f32 v14, -v13, v12, v11
	v_cmp_ge_f32_e64 s[4:5], 0, v14
	v_add_u32_e32 v14, 1, v12
	s_nop 0
	v_cndmask_b32_e64 v13, v12, v13, s[4:5]
	v_fma_f32 v12, -v14, v12, v11
	v_cmp_lt_f32_e64 s[4:5], 0, v12
	s_nop 1
	v_cndmask_b32_e64 v12, v13, v14, s[4:5]
	v_mul_f32_e32 v13, 0x37800000, v12
	v_cndmask_b32_e32 v12, v12, v13, vcc
	v_cmp_class_f32_e32 vcc, v11, v226
	s_nop 1
	v_cndmask_b32_e32 v11, v12, v11, vcc
	v_div_scale_f32 v12, s[4:5], v11, v11, 1.0
	v_rcp_f32_e32 v13, v12
	s_nop 0
	v_fma_f32 v14, -v12, v13, 1.0
	v_fmac_f32_e32 v13, v14, v13
	v_div_scale_f32 v14, vcc, 1.0, v11, 1.0
	v_mul_f32_e32 v15, v14, v13
	v_fma_f32 v16, -v12, v15, v14
	v_fmac_f32_e32 v15, v16, v13
	v_fma_f32 v12, -v12, v15, v14
	v_div_fmas_f32 v12, v12, v13, v15
	v_div_fixup_f32 v11, v12, v11, 1.0
	v_lshl_add_u32 v12, v10, 2, 0
	v_add_u32_e32 v12, 0x20000, v12
	ds_write_b32 v12, v11

; #define PG8_STAGE(bufoff, gbase, voff) do { _Pragma("unroll") for (int _i = 0; _i < 2; ++_i) \
;         __builtin_amdgcn_global_load_lds((const unsigned*)((const char*)(gbase) + (voff)[_i]), (PG8_LAS unsigned*)(lds + (bufoff) + ldsw + _i * 8192), 16, 0, 0); } while (0)
; #define PG8_WAIT_V(n) asm volatile("s_waitcnt vmcnt(" #n ")" ::: "memory")
; #define PG8_BAR __builtin_amdgcn_s_barrier()
; template <class Epi, class Sched, bool ALIGN_EPI = false, bool SP2 = false, bool HALFM = false, bool AMAP = false>
; __device__ __forceinline__ void gemm_phase(PG8_LAS unsigned char* lds, const Gemm g, const Sched& S, const Epi& E, int tid_in) {
;     ...
;     const unsigned ldsw = (unsigned)wid * 1024u;
;     const int aoff = lds_byte(wr * 64 + fr, fq * 8), boff = lds_byte(wc * 32 + fr, fq * 8);
;     ...
;         if (wr == 1) PG8_BAR;
;         if constexpr (HALFM) PG8_WAIT_V(0); else PG8_WAIT_V(2);
;         PG8_BAR;
;         PG8_STAGE(PG8_SB(1, 0), cB + kstep, voffB); PG8_STAGE(PG8_SA(1, 0), cA + kstep, voffA); PG8_STAGE(PG8_SB(1, 1), cB + hstepB + kstep, voffB);
;         PG8_WAIT_V(6); PG8_BAR;
.LBB0_182:
	v_and_b32_e32 v11, 15, v10
	v_lshrrev_b32_e32 v10, 1, v10
	v_and_b32_e32 v10, 24, v10
	v_lshlrev_b32_e32 v12, 1, v10
	s_add_u32 s20, s20, 0x3000000
	v_lshl_or_b32 v125, s4, 6, v11
	v_lshl_or_b32 v12, v11, 6, v12
	v_lshlrev_b32_e32 v11, 2, v11
	s_addc_u32 s21, s21, 0
	s_lshl_b32 s5, s4, 13
	v_and_b32_e32 v13, 32, v11
	v_bitop3_b32 v14, v12, s5, v13 bitop3:0xde
	s_lshl_b32 s5, s18, 5
	s_and_b32 s5, s5, 0x60
	s_lshl_b32 s18, s5, 7
	v_bitop3_b32 v126, v12, s18, v13 bitop3:0xde
	s_waitcnt vmcnt(0)
	s_barrier
	s_mov_b32 s18, s98
	s_cmpk_lt_u32 s23, 0x100
	s_sext_i32_i16 s39, s22
	s_cselect_b64 s[22:23], -1, 0
	s_lshl_b32 s4, s4, 8
	s_waitcnt vmcnt(6)
	s_add_i32 s4, s4, 0
	v_lshlrev_b32_e32 v2, 2, v10
	v_mov_b32_e32 v3, v177
	s_add_i32 s4, s4, 0x20000
	v_lshl_add_u64 v[114:115], s[28:29], 0, v[2:3]
	v_add_u32_e32 v127, s4, v11
	v_or_b32_e32 v128, s5, v10
	s_mov_b32 s38, 0
	v_add_u32_e32 v129, 0, v14
	s_mov_b32 s58, s14
	s_barrier
	s_branch .LBB0_185

; #define PG8_LAS __attribute__((address_space(3)))
; #define PG8_STAGE(bufoff, gbase, voff) do { _Pragma("unroll") for (int _i = 0; _i < 2; ++_i) \
;         __builtin_amdgcn_global_load_lds((const unsigned*)((const char*)(gbase) + (voff)[_i]), (PG8_LAS unsigned*)(lds + (bufoff) + ldsw + _i * 8192), 16, 0, 0); } while (0)
; #define PG8_WAIT_V(n) asm volatile("s_waitcnt vmcnt(" #n ")" ::: "memory")
; #define PG8_BAR __builtin_amdgcn_s_barrier()
; template <class Epi, class Sched, bool ALIGN_EPI = false, bool SP2 = false, bool HALFM = false, bool AMAP = false>
; __device__ __forceinline__ void gemm_phase(PG8_LAS unsigned char* lds, const Gemm g, const Sched& S, const Epi& E, int tid_in) {
;     ...
;     for (int i = 0; i < 2; ++i) { int R, C; stage_rc(tid * 16 + i * 8192, R, C); const int Rb = Epi::PERM ? ((R & ~31) + perm32(R & 31)) : R;
;         const int Ra = AMAP ? (64 * ((R >> 4) & 3) + 16 * (R >> 6) + (R & 15)) : R;
;         voffA[i] = (unsigned)(Ra * g.lda + C) * 2u; voffB[i] = (unsigned)(Rb * g.ldb + C) * 2u; }
;     ...
;     const char* cA = gA + PG8_ATILE(cur.pm); const char* cB = gB + (size_t)cur.pn * tstepB;
;     S.a_ready(cur);
;     if constexpr (SP2) {
;         PG8_STAGE(PG8_SB(0, 0), cB, voffB); PG8_STAGE(PG8_SB(0, 1), cB + hstepB, voffB); PG8_STAGE(PG8_SA(0, 0), cA, voffA); if constexpr (!HALFM) PG8_STAGE(PG8_SA(0, 1), cA + hstepA, voffA);
;         if constexpr (Epi::RSTD) E.prime((PG8_LAS float*)(lds + STAGE_BYTES), cur, tid);
;         if (wr == 1) PG8_BAR;
;         if constexpr (HALFM) PG8_WAIT_V(0); else PG8_WAIT_V(2);
;         PG8_BAR;
;         PG8_STAGE(PG8_SB(1, 0), cB + kstep, voffB); PG8_STAGE(PG8_SA(1, 0), cA + kstep, voffA); PG8_STAGE(PG8_SB(1, 1), cB + hstepB + kstep, voffB);
.LBB0_256:
	s_or_b64 exec, exec, s[4:5]
	s_mov_b64 s[4:5], s[0:1]
	s_waitcnt lgkmcnt(0)
	s_barrier
	s_load_dwordx4 s[12:15], s[4:5], 0xa0
	s_mul_hi_u32 s4, s88, 0x1600000
	s_mul_i32 s88, s88, 0x1600000
	v_readlane_b32 s6, v255, 59
	v_readlane_b32 s7, v255, 60
	s_waitcnt lgkmcnt(0)
	s_add_u32 s16, s14, 0x3000000
	s_addc_u32 s17, s15, 0
	s_add_u32 s5, s14, s88
	s_addc_u32 s4, s15, s4
	s_add_u32 s22, s5, 0x2a800000
	s_addc_u32 s23, s4, 0
	v_readlane_b32 s4, v255, 47
	v_readlane_b32 s5, v255, 48
	s_and_b64 s[20:21], s[4:5], s[6:7]
	v_cndmask_b32_e64 v0, 0, 1, s[20:21]
	s_nop 0
	v_readfirstlane_b32 s4, v0
	s_bitcmp1_b32 s4, 0
	v_readlane_b32 s4, v255, 1
	v_mbcnt_lo_u32_b32 v0, -1, 0
	v_mbcnt_hi_u32_b32 v0, -1, v0
	v_readlane_b32 s5, v255, 2
	v_or_b32_e32 v16, s92, v0
	s_cselect_b64 s[42:43], -1, 0
	v_cndmask_b32_e64 v0, 0, 1, s[4:5]
	v_cmp_ne_u32_e64 s[90:91], 1, v0
	s_andn2_b64 vcc, exec, s[4:5]
	v_readfirstlane_b32 s4, v16
	s_cbranch_vccnz .LBB0_332
	v_lshlrev_b32_e32 v0, 4, v16
	v_add_u32_e32 v1, 0x2000, v0
	v_ashrrev_i32_e32 v2, 31, v1
	v_lshrrev_b32_e32 v2, 22, v2
	v_add_u32_e32 v2, v1, v2
	v_ashrrev_i32_e32 v8, 10, v2
	v_mul_i32_i24_e32 v2, 0x400, v8
	v_sub_u32_e32 v1, v1, v2
	v_lshrrev_b32_e32 v2, 4, v1
	v_bitop3_b32 v1, v2, v1, 32 bitop3:0x6c
	v_ashrrev_i32_e32 v2, 31, v1
	v_lshrrev_b32_e32 v2, 26, v2
	v_add_u32_e32 v2, v1, v2
	v_lshlrev_b32_e32 v3, 3, v8
	v_ashrrev_i32_e32 v9, 6, v2
	v_and_b32_e32 v3, -16, v3
	v_add_u32_e32 v3, v9, v3
	v_and_b32_e32 v4, 3, v9
	s_mov_b32 s7, 0x7fffe0
	v_lshrrev_b32_e32 v5, 2, v3
	v_lshlrev_b32_e32 v6, 1, v3
	v_and_b32_e32 v2, 0xc0, v2
	v_and_or_b32 v4, v3, s7, v4
	v_and_b32_e32 v5, 4, v5
	v_and_b32_e32 v6, 24, v6
	v_sub_u32_e32 v1, v1, v2
	v_or3_b32 v4, v4, v5, v6
	v_lshlrev_b32_e32 v5, 5, v8
	v_ashrrev_i16_sdwa v1, v254, sext(v1) dst_sel:DWORD dst_unused:UNUSED_PAD src0_sel:DWORD src1_sel:BYTE_0
	v_and_b32_e32 v10, 32, v5
	v_bfe_i32 v11, v1, 0, 16
	s_movk_i32 s8, 0x1600
	v_mul_u32_u24_e32 v4, 0x1600, v4
	v_add_u32_e32 v1, v10, v11
	v_mul_lo_u32 v2, v3, s8
	v_add_lshl_u32 v156, v4, v1, 1
	v_add_lshl_u32 v158, v1, v2, 1
	v_bfe_i32 v1, v16, 27, 1
	v_lshrrev_b32_e32 v1, 22, v1
	v_add_u32_e32 v1, v0, v1
	v_and_b32_e32 v1, 0xfffffc00, v1
	v_sub_u32_e32 v0, v0, v1
	v_lshrrev_b32_e32 v1, 4, v0
	v_ashrrev_i32_e32 v2, 31, v16
	v_bitop3_b32 v0, v1, v0, 32 bitop3:0x6c
	v_lshrrev_b32_e32 v2, 26, v2
	v_ashrrev_i32_e32 v1, 31, v0
	v_add_u32_e32 v2, v16, v2
	v_lshrrev_b32_e32 v1, 26, v1
	v_ashrrev_i32_e32 v13, 6, v2
	v_add_u32_e32 v1, v0, v1
	v_lshlrev_b32_e32 v2, 3, v13
	v_ashrrev_i32_e32 v12, 6, v1
	v_and_b32_e32 v2, -16, v2
	v_add_u32_e32 v2, v12, v2
	v_and_b32_e32 v3, 3, v12
	v_lshrrev_b32_e32 v4, 2, v2
	v_lshlrev_b32_e32 v5, 1, v2
	v_and_b32_e32 v1, 0xc0, v1
	v_and_or_b32 v3, v2, s7, v3
	v_and_b32_e32 v4, 4, v4
	v_and_b32_e32 v5, 24, v5
	v_sub_u32_e32 v0, v0, v1
	v_or3_b32 v3, v3, v4, v5
	v_lshlrev_b32_e32 v4, 5, v13
	v_ashrrev_i16_sdwa v0, v254, sext(v0) dst_sel:DWORD dst_unused:UNUSED_PAD src0_sel:DWORD src1_sel:BYTE_0
	v_and_b32_e32 v14, 32, v4
	v_bfe_i32 v15, v0, 0, 16
	v_mul_lo_u32 v1, v2, s8
	v_readlane_b32 s8, v255, 17
	s_ashr_i32 s6, s4, 6
	v_mul_u32_u24_e32 v3, 0x1600, v3
	v_add_u32_e32 v0, v14, v15
	v_readlane_b32 s9, v255, 18
	s_lshl_b32 s18, s6, 10
	v_add_lshl_u32 v176, v3, v0, 1
	v_add_lshl_u32 v160, v0, v1, 1
	v_mov_b64_e32 v[0:1], s[8:9]
	v_lshl_add_u64 v[4:5], s[22:23], 0, v[0:1]
	s_add_i32 s19, s18, 0
	s_add_i32 m0, s19, 0x10000
	v_lshl_add_u64 v[0:1], v[4:5], 0, v[176:177]
	v_mov_b32_e32 v157, v177
	v_readfirstlane_b32 s28, v4
	v_readfirstlane_b32 s29, v5
	global_load_lds_dwordx4 v[0:1], off
	v_lshl_add_u64 v[2:3], v[4:5], 0, v[156:157]
	s_add_i32 m0, s19, 0x12000
	v_lshl_add_u64 v[4:5], v[4:5], 0, s[78:79]
	global_load_lds_dwordx4 v[2:3], off
	s_add_i32 m0, s19, 0x14000
	v_lshl_add_u64 v[6:7], v[4:5], 0, v[176:177]
	v_readlane_b32 s8, v255, 15
	global_load_lds_dwordx4 v[6:7], off
	v_lshl_add_u64 v[4:5], v[4:5], 0, v[156:157]
	s_add_i32 m0, s19, 0x16000
	v_readlane_b32 s9, v255, 16
	global_load_lds_dwordx4 v[4:5], off
	s_nop 0
	v_mov_b64_e32 v[4:5], s[8:9]
	v_lshl_add_u64 v[128:129], s[16:17], 0, v[4:5]
	v_mov_b32_e32 v161, v177
	v_lshl_add_u64 v[4:5], v[128:129], 0, v[160:161]
	s_mov_b32 m0, s19
	v_mov_b32_e32 v159, v177
	s_add_i32 s25, s19, 0x2000
	global_load_lds_dwordx4 v[4:5], off
	v_lshl_add_u64 v[6:7], v[128:129], 0, v[158:159]
	s_mov_b32 m0, s25
	v_lshl_add_u64 v[18:19], v[128:129], 0, s[78:79]
	s_add_i32 s36, s19, 0x4000
	global_load_lds_dwordx4 v[6:7], off
	v_lshl_add_u64 v[20:21], v[18:19], 0, v[160:161]
	s_mov_b32 m0, s36
	s_add_i32 s37, s19, 0x6000
	global_load_lds_dwordx4 v[20:21], off
	v_lshl_add_u64 v[18:19], v[18:19], 0, v[158:159]
	s_mov_b32 m0, s37
	s_ashr_i32 s5, s4, 8
	global_load_lds_dwordx4 v[18:19], off
	s_add_i32 m0, s19, 0x18000
	v_lshl_add_u64 v[0:1], v[0:1], 0, s[66:67]
	global_load_lds_dwordx4 v[0:1], off
	v_lshl_add_u64 v[0:1], v[2:3], 0, s[66:67]
	s_add_i32 m0, s19, 0x1a000
	s_add_i32 s39, s19, 0x8000
	s_add_i32 s60, s19, 0xa000
	global_load_lds_dwordx4 v[0:1], off
	v_lshl_add_u64 v[0:1], v[4:5], 0, s[66:67]
	s_mov_b32 m0, s39
	s_add_u32 s100, s28, 0x160080
	global_load_lds_dwordx4 v[0:1], off
	v_lshl_add_u64 v[0:1], v[6:7], 0, s[66:67]
	s_mov_b32 m0, s60
	s_addc_u32 s101, s29, 0
	global_load_lds_dwordx4 v[0:1], off
	s_add_i32 m0, s19, 0x1c000
	v_lshl_add_u64 v[0:1], s[100:101], 0, v[176:177]
	global_load_lds_dwordx4 v[0:1], off
	v_lshl_add_u64 v[0:1], s[100:101], 0, v[156:157]
	s_add_i32 m0, s19, 0x1e000
	s_nop 0
	global_load_lds_dwordx4 v[0:1], off
	s_cmp_eq_u32 s5, 1
	s_cselect_b64 s[44:45], -1, 0
	s_cmp_lg_u32 s5, 1
	s_cbranch_scc1 .LBB0_259
	s_barrier
; #define PG8_STAGE(bufoff, gbase, voff) do { _Pragma("unroll") for (int _i = 0; _i < 2; ++_i) \
;         __builtin_amdgcn_global_load_lds((const unsigned*)((const char*)(gbase) + (voff)[_i]), (PG8_LAS unsigned*)(lds + (bufoff) + ldsw + _i * 8192), 16, 0, 0); } while (0)
; #define PG8_WAIT_V(n) asm volatile("s_waitcnt vmcnt(" #n ")" ::: "memory")
; #define PG8_BAR __builtin_amdgcn_s_barrier()
; template <class Epi, class Sched, bool ALIGN_EPI = false, bool SP2 = false, bool HALFM = false, bool AMAP = false>
; __device__ __forceinline__ void gemm_phase(PG8_LAS unsigned char* lds, const Gemm g, const Sched& S, const Epi& E, int tid_in) {
;     ...
;     const unsigned ldsw = (unsigned)wid * 1024u;
;     const int aoff = lds_byte(wr * 64 + fr, fq * 8), boff = lds_byte(wc * 32 + fr, fq * 8);
;     ...
;         if (wr == 1) PG8_BAR;
;         if constexpr (HALFM) PG8_WAIT_V(0); else PG8_WAIT_V(2);
;         PG8_BAR;
;         PG8_STAGE(PG8_SB(1, 0), cB + kstep, voffB); PG8_STAGE(PG8_SA(1, 0), cA + kstep, voffA); PG8_STAGE(PG8_SB(1, 1), cB + hstepB + kstep, voffB);
;         PG8_WAIT_V(6); PG8_BAR;
.LBB0_259:
	s_add_u32 s46, s14, 0x1000000
	s_addc_u32 s47, s15, 0
	v_bfe_u32 v17, v16, 4, 2
	s_add_u32 s14, s14, 0x300000
	v_and_b32_e32 v18, 15, v16
	v_lshlrev_b32_e32 v19, 4, v17
	v_lshlrev_b32_e32 v16, 2, v16
	s_addc_u32 s15, s15, 0
	s_and_b32 s38, s6, 3
	v_lshl_or_b32 v192, s5, 6, v18
	v_lshl_or_b32 v18, v18, 6, v19
	s_lshl_b32 s5, s5, 13
	v_and_b32_e32 v16, 32, v16
	v_bitop3_b32 v19, v18, s5, v16 bitop3:0xde
	s_lshl_b32 s5, s38, 5
	s_lshl_b32 s6, s38, 12
	s_waitcnt vmcnt(2)
	s_barrier
	v_bitop3_b32 v193, v18, s6, v16 bitop3:0xde
	s_mov_b32 s6, s100
	s_mov_b32 s7, s101
	s_movk_i32 s9, 0x1600
	v_lshrrev_b32_e32 v1, 1, v8
	v_mul_lo_u32 v0, v9, s9
	s_mov_b32 s8, 0x16000
	s_cmpk_lt_u32 s4, 0x100
	v_lshl_or_b32 v194, v17, 3, s5
	v_mad_u64_u32 v[0:1], s[4:5], v1, s8, v[0:1]
	v_or_b32_e32 v0, v0, v10
	v_add_lshl_u32 v0, v0, v11, 1
	v_mov_b32_e32 v1, v177
	s_mov_b64 s[10:11], 0x160080
	v_lshl_add_u64 v[162:163], v[0:1], 0, s[10:11]
	v_lshrrev_b32_e32 v1, 1, v13
	v_mul_lo_u32 v0, v12, s9
	v_mad_u64_u32 v[0:1], s[4:5], v1, s8, v[0:1]
	s_waitcnt vmcnt(6)
	v_or_b32_e32 v0, v0, v14
	v_add_lshl_u32 v0, v0, v15, 1
	v_mov_b32_e32 v1, v177
	v_readlane_b32 s4, v255, 25
	s_cselect_b64 s[48:49], -1, 0
	s_mov_b32 s61, 0
	v_cmp_eq_u32_e64 s[6:7], 0, v17
	v_lshl_add_u64 v[164:165], v[0:1], 0, s[10:11]
	v_add_u32_e32 v195, 0, v19
	v_readlane_b32 s80, v255, 13
	s_mov_b32 s81, s4
	s_barrier
	v_readlane_b32 s5, v255, 26
	s_branch .LBB0_262

; #define PG8_LAS __attribute__((address_space(3)))
; #define PG8_STAGE(bufoff, gbase, voff) do { _Pragma("unroll") for (int _i = 0; _i < 2; ++_i) \
;         __builtin_amdgcn_global_load_lds((const unsigned*)((const char*)(gbase) + (voff)[_i]), (PG8_LAS unsigned*)(lds + (bufoff) + ldsw + _i * 8192), 16, 0, 0); } while (0)
; #define PG8_WAIT_V(n) asm volatile("s_waitcnt vmcnt(" #n ")" ::: "memory")
; #define PG8_BAR __builtin_amdgcn_s_barrier()
; template <class Epi, class Sched, bool ALIGN_EPI = false, bool SP2 = false, bool HALFM = false, bool AMAP = false>
; __device__ __forceinline__ void gemm_phase(PG8_LAS unsigned char* lds, const Gemm g, const Sched& S, const Epi& E, int tid_in) {
;     ...
;     for (int i = 0; i < 2; ++i) { int R, C; stage_rc(tid * 16 + i * 8192, R, C); const int Rb = Epi::PERM ? ((R & ~31) + perm32(R & 31)) : R;
;         const int Ra = AMAP ? (64 * ((R >> 4) & 3) + 16 * (R >> 6) + (R & 15)) : R;
;         voffA[i] = (unsigned)(Ra * g.lda + C) * 2u; voffB[i] = (unsigned)(Rb * g.ldb + C) * 2u; }
;     const size_t kstep = (size_t)(BK * 2);
;     const size_t hstepA = (size_t)(AMAP ? 256 : HALF) * g.lda * 2, hstepB = (size_t)HALF * g.ldb * 2;
;     ...
;     const char* cA = gA + PG8_ATILE(cur.pm); const char* cB = gB + (size_t)cur.pn * tstepB;
;     S.a_ready(cur);
;     if constexpr (SP2) {
;         PG8_STAGE(PG8_SB(0, 0), cB, voffB); PG8_STAGE(PG8_SB(0, 1), cB + hstepB, voffB); PG8_STAGE(PG8_SA(0, 0), cA, voffA); if constexpr (!HALFM) PG8_STAGE(PG8_SA(0, 1), cA + hstepA, voffA);
;         if constexpr (Epi::RSTD) E.prime((PG8_LAS float*)(lds + STAGE_BYTES), cur, tid);
;         if (wr == 1) PG8_BAR;
;         if constexpr (HALFM) PG8_WAIT_V(0); else PG8_WAIT_V(2);
;         PG8_BAR;
;         PG8_STAGE(PG8_SB(1, 0), cB + kstep, voffB); PG8_STAGE(PG8_SA(1, 0), cA + kstep, voffA); PG8_STAGE(PG8_SB(1, 1), cB + hstepB + kstep, voffB);
.LBB0_385:
	s_or_b64 exec, exec, s[6:7]
	s_andn2_b64 vcc, exec, s[40:41]
	s_mov_b64 s[6:7], -1
	s_waitcnt lgkmcnt(0)
	s_barrier
	s_cbranch_vccnz .LBB0_151
	s_mov_b64 s[6:7], s[0:1]
	s_load_dwordx2 s[40:41], s[6:7], 0xa8
	v_readlane_b32 s4, v255, 49
	v_readlane_b32 s5, v255, 50
	v_mbcnt_lo_u32_b32 v0, -1, 0
	v_mbcnt_hi_u32_b32 v0, -1, v0
	s_waitcnt lgkmcnt(0)
	s_add_u32 s42, s40, 0x1000000
	s_addc_u32 s43, s41, 0
	s_add_u32 s4, s40, s4
	s_addc_u32 s5, s41, s5
	s_add_u32 s44, s4, 0x35800000
	s_addc_u32 s45, s5, 0
	v_readlane_b32 s4, v255, 3
	v_or_b32_e32 v17, s92, v0
	v_readlane_b32 s5, v255, 4
	s_andn2_b64 vcc, exec, s[4:5]
	v_readfirstlane_b32 s4, v17
	s_cbranch_vccnz .LBB0_424
	v_lshlrev_b32_e32 v0, 4, v17
	v_add_u32_e32 v1, 0x2000, v0
	v_ashrrev_i32_e32 v2, 31, v1
	v_lshrrev_b32_e32 v2, 22, v2
	v_add_u32_e32 v2, v1, v2
	v_ashrrev_i32_e32 v9, 10, v2
	v_mul_i32_i24_e32 v2, 0x400, v9
	v_sub_u32_e32 v1, v1, v2
	v_lshrrev_b32_e32 v2, 4, v1
	v_bitop3_b32 v1, v2, v1, 32 bitop3:0x6c
	v_ashrrev_i32_e32 v2, 31, v1
	v_lshrrev_b32_e32 v2, 26, v2
	v_add_u32_e32 v2, v1, v2
	v_lshlrev_b32_e32 v4, 3, v9
	v_ashrrev_i32_e32 v3, 6, v2
	v_and_b32_e32 v4, -16, v4
	v_add_u32_e32 v4, v3, v4
	s_load_dwordx4 s[12:15], s[6:7], 0x40
	v_and_b32_e32 v5, 3, v3
	s_mov_b32 s6, 0xfffe0
	v_lshrrev_b32_e32 v6, 2, v4
	v_lshlrev_b32_e32 v10, 1, v4
	v_and_b32_e32 v2, 0xc0, v2
	v_and_or_b32 v5, v4, s6, v5
	v_and_b32_e32 v7, 4, v6
	v_and_b32_e32 v10, 24, v10
	v_sub_u32_e32 v1, v1, v2
	v_lshlrev_b32_e32 v2, 2, v4
	v_or3_b32 v5, v5, v7, v10
	v_lshlrev_b32_e32 v7, 5, v9
	v_ashrrev_i16_sdwa v1, v254, sext(v1) dst_sel:DWORD dst_unused:UNUSED_PAD src0_sel:DWORD src1_sel:BYTE_0
	v_and_b32_e32 v2, 0xc0, v2
	v_and_b32_e32 v4, 0xffff0, v6
	v_and_b32_e32 v7, 32, v7
	v_bfe_i32 v10, v1, 0, 16
	v_add_u32_e32 v11, v2, v4
	v_and_b32_e32 v12, 15, v3
	v_add_lshl_u32 v1, v7, v10, 1
	v_or_b32_e32 v2, v11, v12
	v_lshl_add_u32 v184, v5, 12, v1
	v_lshl_add_u32 v186, v2, 12, v1
	v_bfe_i32 v1, v17, 27, 1
	v_lshrrev_b32_e32 v1, 22, v1
	v_add_u32_e32 v1, v0, v1
	v_and_b32_e32 v1, 0xfffffc00, v1
	v_sub_u32_e32 v0, v0, v1
	v_lshrrev_b32_e32 v1, 4, v0
	v_ashrrev_i32_e32 v3, 31, v17
	v_bitop3_b32 v0, v1, v0, 32 bitop3:0x6c
	v_lshrrev_b32_e32 v3, 26, v3
	v_ashrrev_i32_e32 v1, 31, v0
	v_add_u32_e32 v3, v17, v3
	v_lshrrev_b32_e32 v1, 26, v1
	v_ashrrev_i32_e32 v13, 6, v3
	v_add_u32_e32 v1, v0, v1
	v_lshlrev_b32_e32 v3, 3, v13
	v_ashrrev_i32_e32 v2, 6, v1
	v_and_b32_e32 v3, -16, v3
	v_add_u32_e32 v3, v2, v3
	v_and_b32_e32 v4, 3, v2
	v_lshrrev_b32_e32 v5, 2, v3
	v_lshlrev_b32_e32 v7, 1, v3
	v_and_b32_e32 v1, 0xc0, v1
	v_writelane_b32 v255, s90, 61
	v_and_or_b32 v4, v3, s6, v4
	v_and_b32_e32 v6, 4, v5
	v_and_b32_e32 v7, 24, v7
	v_sub_u32_e32 v0, v0, v1
	v_lshlrev_b32_e32 v1, 2, v3
	v_writelane_b32 v255, s91, 62
	v_or3_b32 v4, v4, v6, v7
	v_lshlrev_b32_e32 v6, 5, v13
	v_ashrrev_i16_sdwa v0, v254, sext(v0) dst_sel:DWORD dst_unused:UNUSED_PAD src0_sel:DWORD src1_sel:BYTE_0
	v_and_b32_e32 v1, 0xc0, v1
	v_and_b32_e32 v3, 0xffff0, v5
	s_add_u32 s46, s40, 0x300000
	v_and_b32_e32 v6, 32, v6
	v_bfe_i32 v14, v0, 0, 16
	v_add_u32_e32 v15, v1, v3
	v_and_b32_e32 v16, 15, v2
	v_readlane_b32 s6, v255, 23
	s_addc_u32 s47, s41, 0
	s_ashr_i32 s5, s4, 6
	v_add_lshl_u32 v0, v6, v14, 1
	v_or_b32_e32 v1, v15, v16
	v_readlane_b32 s7, v255, 24
	s_lshl_b32 s25, s5, 10
	v_lshl_add_u32 v176, v4, 12, v0
	v_lshl_add_u32 v188, v1, 12, v0
	v_mov_b64_e32 v[0:1], s[6:7]
	v_lshl_add_u64 v[4:5], s[44:45], 0, v[0:1]
	s_add_i32 s38, s25, 0
	s_add_i32 m0, s38, 0x10000
	v_lshl_add_u64 v[0:1], v[4:5], 0, v[176:177]
	v_mov_b32_e32 v185, v177
	s_mov_b64 s[6:7], 0x80000
	v_readfirstlane_b32 s28, v4
	v_readfirstlane_b32 s29, v5
	global_load_lds_dwordx4 v[0:1], off
	v_lshl_add_u64 v[2:3], v[4:5], 0, v[184:185]
	s_add_i32 m0, s38, 0x12000
	v_lshl_add_u64 v[4:5], v[4:5], 0, s[6:7]
	global_load_lds_dwordx4 v[2:3], off
	s_add_i32 m0, s38, 0x14000
	v_lshl_add_u64 v[6:7], v[4:5], 0, v[176:177]
	v_readlane_b32 s6, v255, 21
	global_load_lds_dwordx4 v[6:7], off
	v_lshl_add_u64 v[4:5], v[4:5], 0, v[184:185]
	s_add_i32 m0, s38, 0x16000
	v_readlane_b32 s7, v255, 22
	global_load_lds_dwordx4 v[4:5], off
	s_nop 0
	v_mov_b64_e32 v[4:5], s[6:7]
	v_lshl_add_u64 v[18:19], s[42:43], 0, v[4:5]
	v_mov_b32_e32 v189, v177
	v_lshl_add_u64 v[4:5], v[18:19], 0, v[188:189]
	s_mov_b32 m0, s38
	v_mov_b32_e32 v187, v177
	s_add_i32 s39, s38, 0x2000
	s_mov_b64 s[6:7], 0x100000
	v_readfirstlane_b32 s30, v18
	v_readfirstlane_b32 s31, v19
	global_load_lds_dwordx4 v[4:5], off
	v_lshl_add_u64 v[6:7], v[18:19], 0, v[186:187]
	s_mov_b32 m0, s39
	v_lshl_add_u64 v[18:19], v[18:19], 0, s[6:7]
	s_add_i32 s88, s38, 0x4000
	global_load_lds_dwordx4 v[6:7], off
	v_lshl_add_u64 v[20:21], v[18:19], 0, v[188:189]
	s_mov_b32 m0, s88
	s_add_i32 s90, s38, 0x6000
	global_load_lds_dwordx4 v[20:21], off
	v_lshl_add_u64 v[18:19], v[18:19], 0, v[186:187]
	s_mov_b32 m0, s90
	v_and_b32_e32 v8, 15, v17
	global_load_lds_dwordx4 v[18:19], off
	s_add_i32 m0, s38, 0x18000
	v_lshl_add_u64 v[0:1], v[0:1], 0, s[66:67]
	global_load_lds_dwordx4 v[0:1], off
	v_lshl_add_u64 v[0:1], v[2:3], 0, s[66:67]
	s_add_i32 m0, s38, 0x1a000
	s_add_i32 s18, s38, 0x8000
	s_add_i32 s19, s38, 0xa000
	global_load_lds_dwordx4 v[0:1], off
	v_lshl_add_u64 v[0:1], v[4:5], 0, s[66:67]
	s_mov_b32 m0, s18
	s_add_u32 s100, s28, 0x80080
	global_load_lds_dwordx4 v[0:1], off
	v_lshl_add_u64 v[0:1], v[6:7], 0, s[66:67]
	s_mov_b32 m0, s19
	s_addc_u32 s101, s29, 0
	global_load_lds_dwordx4 v[0:1], off
	s_add_i32 m0, s38, 0x1c000
	v_lshl_add_u64 v[0:1], s[100:101], 0, v[176:177]
	global_load_lds_dwordx4 v[0:1], off
	v_lshl_add_u64 v[0:1], s[100:101], 0, v[184:185]
	s_add_i32 m0, s38, 0x1e000
	s_nop 0
	global_load_lds_dwordx4 v[0:1], off
	v_bfe_u32 v232, v17, 4, 2
	v_cmp_gt_i32_e32 vcc, s89, v17
	s_and_saveexec_b64 s[8:9], vcc
	s_cbranch_execz .LBB0_389
; #define PG8_LAS __attribute__((address_space(3)))
; __device__ __forceinline__ float row_rstd(const float* ssq, int row) {
;     const f32x4* p = (const f32x4*)(ssq + (size_t)row * 32); f32x4 v[8];
; #pragma unroll
;     for (int i = 0; i < 8; ++i) v[i] = p[i];
;     float s = 0.f;
; #pragma unroll
;     for (int i = 0; i < 8; ++i) s += (v[i][0] + v[i][1]) + (v[i][2] + v[i][3]);
;     return 1.0f / sqrtf(s * (1.0f / 2048.0f) + 1e-6f);
; }
;     __device__ __forceinline__ void prime(PG8_LAS float* rc, const Unit& u, int tid) const {
;         if (tid < BM) { const int ai = tid >> 7, wr_ = (tid >> 6) & 1, m = (tid >> 4) & 3, fr_ = tid & 15; rc[tid] = row_rstd(ssq, 512 * (u.pm & 15) + 32 * (u.pm >> 4) + 64 * (4 * ai + m) + 16 * wr_ + fr_); }
;         asm volatile("s_waitcnt lgkmcnt(0)" ::: "memory");
	v_lshrrev_b32_e32 v18, 5, v17
	s_mov_b32 s6, 0x3fffffc
	v_and_or_b32 v18, v18, s6, v232
	v_lshrrev_b32_e32 v19, 2, v17
	v_lshlrev_b32_e32 v18, 6, v18
	v_and_b32_e32 v19, 16, v19
	v_or3_b32 v18, v19, v18, v8
	v_readlane_b32 s6, v255, 19
	v_readlane_b32 s7, v255, 20
	v_lshl_add_u32 v17, v17, 2, 0
	v_add_u32_e32 v18, s6, v18
	v_ashrrev_i32_e32 v19, 31, v18
	v_lshlrev_b64 v[18:19], 7, v[18:19]
	v_lshl_add_u64 v[46:47], s[46:47], 0, v[18:19]
	global_load_dwordx4 v[18:21], v[46:47], off offset:48
	global_load_dwordx4 v[22:25], v[46:47], off offset:32
	global_load_dwordx4 v[26:29], v[46:47], off
	global_load_dwordx4 v[30:33], v[46:47], off offset:16
	global_load_dwordx4 v[34:37], v[46:47], off offset:112
	global_load_dwordx4 v[38:41], v[46:47], off offset:96
	global_load_dwordx4 v[42:45], v[46:47], off offset:80
	s_nop 0
	global_load_dwordx4 v[46:49], v[46:47], off offset:64
	v_add_u32_e32 v17, 0x20000, v17
	s_waitcnt vmcnt(0)
	v_add_f32_e32 v18, v18, v19
	v_add_f32_e32 v20, v20, v21
	v_mov_b32_e32 v50, v26
	v_mov_b32_e32 v51, v30
	v_mov_b32_e32 v30, v27
	v_pk_add_f32 v[26:27], v[50:51], v[30:31]
	v_mov_b32_e32 v30, v28
	v_mov_b32_e32 v31, v32
	v_mov_b32_e32 v32, v29
	v_pk_add_f32 v[28:29], v[30:31], v[32:33]
	v_mov_b32_e32 v19, v48
	v_pk_add_f32 v[26:27], v[26:27], v[28:29]
	v_mov_b32_e32 v28, v23
	v_mov_b32_e32 v29, v24
	v_mov_b32_e32 v23, v25
	v_pk_add_f32 v[22:23], v[28:29], v[22:23]
	v_add_f32_e32 v26, 0, v26
	v_pk_add_f32 v[22:23], v[22:23], v[22:23] op_sel:[0,1] op_sel_hi:[1,0]
	v_add_f32_e32 v26, v26, v27
	v_mov_b32_e32 v27, v46
	v_mov_b32_e32 v23, v47
	v_mov_b32_e32 v21, v49
	v_pk_add_f32 v[22:23], v[26:27], v[22:23]
	v_pk_add_f32 v[18:19], v[18:19], v[20:21]
	v_mov_b32_e32 v20, v43
	v_mov_b32_e32 v21, v44
	v_mov_b32_e32 v43, v45
	v_pk_add_f32 v[18:19], v[22:23], v[18:19]
	v_pk_add_f32 v[20:21], v[20:21], v[42:43]
	v_pk_add_f32 v[18:19], v[18:19], v[18:19] op_sel:[0,1] op_sel_hi:[1,0]
	v_pk_add_f32 v[20:21], v[20:21], v[20:21] op_sel:[0,1] op_sel_hi:[1,0]
	v_add_f32_e32 v22, v38, v39
	v_add_f32_e32 v24, v40, v41
	v_mov_b32_e32 v19, v34
	v_mov_b32_e32 v21, v35
	v_mov_b32_e32 v23, v36
	v_mov_b32_e32 v25, v37
	v_pk_add_f32 v[18:19], v[18:19], v[20:21]
	v_pk_add_f32 v[20:21], v[22:23], v[24:25]
	s_nop 0
	v_pk_add_f32 v[18:19], v[18:19], v[20:21]
	s_nop 0
	v_add_f32_e32 v18, v18, v19
	v_fmamk_f32 v18, v18, 0x3a000000, v221
	v_cmp_gt_f32_e32 vcc, s52, v18
	v_mul_f32_e32 v19, 0x4f800000, v18
	s_nop 0
	v_cndmask_b32_e32 v18, v18, v19, vcc
	v_sqrt_f32_e32 v19, v18
	s_nop 0
	v_add_u32_e32 v20, -1, v19
	v_fma_f32 v21, -v20, v19, v18
	v_cmp_ge_f32_e64 s[6:7], 0, v21
	v_add_u32_e32 v21, 1, v19
	s_nop 0
	v_cndmask_b32_e64 v20, v19, v20, s[6:7]
	v_fma_f32 v19, -v21, v19, v18
	v_cmp_lt_f32_e64 s[6:7], 0, v19
	s_nop 1
	v_cndmask_b32_e64 v19, v20, v21, s[6:7]
	v_mul_f32_e32 v20, 0x37800000, v19
	v_cndmask_b32_e32 v19, v19, v20, vcc
	v_cmp_class_f32_e32 vcc, v18, v226
	s_nop 1
	v_cndmask_b32_e32 v18, v19, v18, vcc
	v_div_scale_f32 v19, s[6:7], v18, v18, 1.0
	v_rcp_f32_e32 v20, v19
	s_nop 0
	v_fma_f32 v21, -v19, v20, 1.0
	v_fmac_f32_e32 v20, v21, v20
	v_div_scale_f32 v21, vcc, 1.0, v18, 1.0
	v_mul_f32_e32 v22, v21, v20
	v_fma_f32 v23, -v19, v22, v21
	v_fmac_f32_e32 v22, v23, v20
	v_fma_f32 v19, -v19, v22, v21
	v_div_fmas_f32 v19, v19, v20, v22
	v_div_fixup_f32 v18, v19, v18, 1.0
	ds_write_b32 v17, v18

; #define PG8_STAGE(bufoff, gbase, voff) do { _Pragma("unroll") for (int _i = 0; _i < 2; ++_i) \
;         __builtin_amdgcn_global_load_lds((const unsigned*)((const char*)(gbase) + (voff)[_i]), (PG8_LAS unsigned*)(lds + (bufoff) + ldsw + _i * 8192), 16, 0, 0); } while (0)
; #define PG8_WAIT_V(n) asm volatile("s_waitcnt vmcnt(" #n ")" ::: "memory")
; #define PG8_BAR __builtin_amdgcn_s_barrier()
; template <class Epi, class Sched, bool ALIGN_EPI = false, bool SP2 = false, bool HALFM = false, bool AMAP = false>
; __device__ __forceinline__ void gemm_phase(PG8_LAS unsigned char* lds, const Gemm g, const Sched& S, const Epi& E, int tid_in) {
;     ...
;     const unsigned ldsw = (unsigned)wid * 1024u;
;     const int aoff = lds_byte(wr * 64 + fr, fq * 8), boff = lds_byte(wc * 32 + fr, fq * 8);
;     ...
;         if (wr == 1) PG8_BAR;
;         if constexpr (HALFM) PG8_WAIT_V(0); else PG8_WAIT_V(2);
;         PG8_BAR;
;         PG8_STAGE(PG8_SB(1, 0), cB + kstep, voffB); PG8_STAGE(PG8_SA(1, 0), cA + kstep, voffA); PG8_STAGE(PG8_SB(1, 1), cB + hstepB + kstep, voffB);
;         PG8_WAIT_V(6); PG8_BAR;
.LBB0_391:
	s_add_u32 s58, s40, 0x9800000
	s_addc_u32 s59, s41, 0
	s_add_u32 s60, s40, 0x11800000
	s_addc_u32 s61, s41, 0
	s_add_u32 s62, s40, 0x100000
	s_addc_u32 s63, s41, 0
	s_add_u32 s20, s40, 0x200000
	v_lshlrev_b32_e32 v17, 6, v8
	v_lshlrev_b32_e32 v18, 2, v8
	s_addc_u32 s21, s41, 0
	s_and_b32 s91, s5, 3
	v_lshl_or_b32 v17, v232, 4, v17
	s_lshl_b32 s5, s6, 13
	v_and_b32_e32 v19, 32, v18
	v_bitop3_b32 v20, v17, s5, v19 bitop3:0xde
	s_lshl_b32 s89, s91, 5
	s_lshl_b32 s5, s91, 12
	s_waitcnt vmcnt(2)
	s_barrier
	s_mov_b32 s8, s100
	s_mov_b32 s9, s101
	s_cmpk_lt_u32 s4, 0x100
	v_and_b32_e32 v1, 1, v9
	v_add_u32_e32 v0, v11, v12
	v_lshlrev_b32_e32 v1, 6, v1
	s_cselect_b64 s[22:23], -1, 0
	s_and_b32 s4, s4, 0xffffff00
	v_lshl_or_b32 v0, v0, 12, v1
	v_and_b32_e32 v1, 1, v13
	s_waitcnt vmcnt(6)
	s_add_i32 s4, s4, 0
	v_lshl_add_u32 v190, v10, 1, v0
	v_add_u32_e32 v0, v15, v16
	v_lshlrev_b32_e32 v1, 6, v1
	s_add_i32 s4, s4, 0x20000
	v_lshl_or_b32 v0, v0, 12, v1
	v_bitop3_b32 v233, v17, s5, v19 bitop3:0xde
	v_lshl_or_b32 v254, s6, 4, v8
	v_add_u32_e32 v227, s4, v18
	s_lshl_b32 s94, s91, 11
	v_mov_b32_e32 v191, v177
	v_lshl_add_u32 v192, v14, 1, v0
	v_mov_b32_e32 v193, v177
	s_mov_b32 s95, 0
	v_add_u32_e32 v236, 0, v20
	v_readlane_b32 s11, v255, 14
	s_mov_b32 s10, s35
	s_barrier
	s_branch .LBB0_394

; #define PG8_LAS __attribute__((address_space(3)))
; #define PG8_STAGE(bufoff, gbase, voff) do { _Pragma("unroll") for (int _i = 0; _i < 2; ++_i) \
;         __builtin_amdgcn_global_load_lds((const unsigned*)((const char*)(gbase) + (voff)[_i]), (PG8_LAS unsigned*)(lds + (bufoff) + ldsw + _i * 8192), 16, 0, 0); } while (0)
; #define PG8_WAIT_V(n) asm volatile("s_waitcnt vmcnt(" #n ")" ::: "memory")
; #define PG8_BAR __builtin_amdgcn_s_barrier()
; template <class Epi, class Sched, bool ALIGN_EPI = false, bool SP2 = false, bool HALFM = false, bool AMAP = false>
; __device__ __forceinline__ void gemm_phase(PG8_LAS unsigned char* lds, const Gemm g, const Sched& S, const Epi& E, int tid_in) {
;     ...
;     const char* cA = gA + PG8_ATILE(cur.pm); const char* cB = gB + (size_t)cur.pn * tstepB;
;     S.a_ready(cur);
;     if constexpr (SP2) {
;         PG8_STAGE(PG8_SB(0, 0), cB, voffB); PG8_STAGE(PG8_SB(0, 1), cB + hstepB, voffB); PG8_STAGE(PG8_SA(0, 0), cA, voffA); if constexpr (!HALFM) PG8_STAGE(PG8_SA(0, 1), cA + hstepA, voffA);
;         if constexpr (Epi::RSTD) E.prime((PG8_LAS float*)(lds + STAGE_BYTES), cur, tid);
;         if (wr == 1) PG8_BAR;
;         if constexpr (HALFM) PG8_WAIT_V(0); else PG8_WAIT_V(2);
;         PG8_BAR;
;         PG8_STAGE(PG8_SB(1, 0), cB + kstep, voffB); PG8_STAGE(PG8_SA(1, 0), cA + kstep, voffA); PG8_STAGE(PG8_SB(1, 1), cB + hstepB + kstep, voffB);
;         PG8_WAIT_V(6); PG8_BAR;
.LBB0_477:
	s_or_b64 exec, exec, s[6:7]
	s_mov_b64 s[4:5], s[0:1]
	s_waitcnt lgkmcnt(0)
	s_barrier
	s_load_dwordx2 s[6:7], s[4:5], 0xa8
	v_mbcnt_lo_u32_b32 v0, -1, 0
	v_mbcnt_hi_u32_b32 v0, -1, v0
	s_waitcnt lgkmcnt(0)
	s_add_u32 s8, s6, 0x400000
	s_addc_u32 s9, s7, 0
	s_add_u32 s12, s6, 0x9800000
	s_addc_u32 s13, s7, 0
	v_or_b32_e32 v12, s92, v0
	s_and_b64 vcc, exec, s[90:91]
	v_readfirstlane_b32 s5, v12
	s_cbranch_vccnz .LBB0_495
	v_lshlrev_b32_e32 v0, 4, v12
	v_add_u32_e32 v1, 0x2000, v0
	v_ashrrev_i32_e32 v2, 31, v1
	v_lshrrev_b32_e32 v2, 22, v2
	v_add_u32_e32 v2, v1, v2
	v_ashrrev_i32_e32 v2, 10, v2
	v_mul_i32_i24_e32 v3, 0x400, v2
	v_sub_u32_e32 v1, v1, v3
	v_lshrrev_b32_e32 v3, 4, v1
	v_bitop3_b32 v1, v3, v1, 32 bitop3:0x6c
	v_ashrrev_i32_e32 v3, 31, v1
	v_lshrrev_b32_e32 v3, 26, v3
	v_add_u32_e32 v3, v1, v3
	v_lshlrev_b32_e32 v5, 3, v2
	v_ashrrev_i32_e32 v4, 6, v3
	v_and_b32_e32 v5, -16, v5
	v_and_b32_e32 v3, 0xc0, v3
	v_add_u32_e32 v5, v4, v5
	v_sub_u32_e32 v1, v1, v3
	v_and_b32_e32 v4, 3, v4
	v_lshrrev_b32_e32 v6, 2, v5
	v_lshlrev_b32_e32 v7, 1, v5
	v_lshlrev_b32_e32 v2, 5, v2
	v_ashrrev_i16_sdwa v1, v254, sext(v1) dst_sel:DWORD dst_unused:UNUSED_PAD src0_sel:DWORD src1_sel:BYTE_0
	v_and_or_b32 v4, v5, s86, v4
	v_and_b32_e32 v6, 4, v6
	v_and_b32_e32 v7, 24, v7
	v_and_b32_e32 v2, 32, v2
	v_bfe_i32 v1, v1, 0, 16
	v_or3_b32 v4, v4, v6, v7
	v_add_lshl_u32 v1, v2, v1, 1
	v_lshl_add_u32 v140, v4, 8, v1
	v_lshl_add_u32 v142, v5, 8, v1
	v_bfe_i32 v1, v12, 27, 1
	v_lshrrev_b32_e32 v1, 22, v1
	v_add_u32_e32 v1, v0, v1
	v_and_b32_e32 v1, 0xfffffc00, v1
	v_sub_u32_e32 v0, v0, v1
	v_lshrrev_b32_e32 v1, 4, v0
	v_ashrrev_i32_e32 v3, 31, v12
	v_bitop3_b32 v0, v1, v0, 32 bitop3:0x6c
	v_lshrrev_b32_e32 v3, 26, v3
	v_ashrrev_i32_e32 v1, 31, v0
	v_add_u32_e32 v3, v12, v3
	v_lshrrev_b32_e32 v1, 26, v1
	v_ashrrev_i32_e32 v3, 6, v3
	v_add_u32_e32 v1, v0, v1
	v_lshlrev_b32_e32 v4, 3, v3
	v_ashrrev_i32_e32 v2, 6, v1
	v_and_b32_e32 v4, -16, v4
	v_and_b32_e32 v1, 0xc0, v1
	v_add_u32_e32 v4, v2, v4
	v_sub_u32_e32 v0, v0, v1
	v_and_b32_e32 v2, 3, v2
	v_lshrrev_b32_e32 v5, 2, v4
	v_lshlrev_b32_e32 v6, 1, v4
	v_lshlrev_b32_e32 v3, 5, v3
	v_ashrrev_i16_sdwa v0, v254, sext(v0) dst_sel:DWORD dst_unused:UNUSED_PAD src0_sel:DWORD src1_sel:BYTE_0
	v_and_or_b32 v2, v4, s86, v2
	v_and_b32_e32 v5, 4, v5
	v_and_b32_e32 v6, 24, v6
	v_and_b32_e32 v3, 32, v3
	v_bfe_i32 v0, v0, 0, 16
	v_readlane_b32 s14, v255, 38
	s_ashr_i32 s4, s5, 6
	v_or3_b32 v2, v2, v5, v6
	v_add_lshl_u32 v0, v3, v0, 1
	v_readlane_b32 s15, v255, 39
	s_lshl_b32 s10, s4, 10
	v_lshl_add_u32 v176, v2, 8, v0
	v_lshl_add_u32 v144, v4, 8, v0
	v_mov_b64_e32 v[0:1], s[14:15]
	v_lshl_add_u64 v[0:1], s[12:13], 0, v[0:1]
	s_add_i32 s11, s10, 0
	s_add_i32 m0, s11, 0x10000
	v_lshl_add_u64 v[4:5], v[0:1], 0, v[176:177]
	v_mov_b32_e32 v141, v177
	global_load_lds_dwordx4 v[4:5], off
	v_lshl_add_u64 v[6:7], v[0:1], 0, v[140:141]
	s_add_i32 m0, s11, 0x12000
	v_lshl_add_u64 v[2:3], v[0:1], 0, s[82:83]
	global_load_lds_dwordx4 v[6:7], off
	s_add_i32 m0, s11, 0x14000
	v_lshl_add_u64 v[8:9], v[2:3], 0, v[176:177]
	v_readlane_b32 s14, v255, 36
	global_load_lds_dwordx4 v[8:9], off
	v_lshl_add_u64 v[2:3], v[2:3], 0, v[140:141]
	s_add_i32 m0, s11, 0x16000
	v_readlane_b32 s15, v255, 37
	global_load_lds_dwordx4 v[2:3], off
	s_nop 0
	v_mov_b64_e32 v[2:3], s[14:15]
	v_lshl_add_u64 v[2:3], s[8:9], 0, v[2:3]
	v_mov_b32_e32 v145, v177
	v_lshl_add_u64 v[8:9], v[2:3], 0, v[144:145]
	s_mov_b32 m0, s11
	v_mov_b32_e32 v143, v177
	s_add_i32 s18, s11, 0x2000
	global_load_lds_dwordx4 v[8:9], off
	v_lshl_add_u64 v[10:11], v[2:3], 0, v[142:143]
	s_mov_b32 m0, s18
	v_lshl_add_u64 v[14:15], v[2:3], 0, s[82:83]
	s_add_i32 s19, s11, 0x4000
	global_load_lds_dwordx4 v[10:11], off
	v_lshl_add_u64 v[16:17], v[14:15], 0, v[144:145]
	s_mov_b32 m0, s19
	s_add_i32 s25, s11, 0x6000
	global_load_lds_dwordx4 v[16:17], off
	v_lshl_add_u64 v[14:15], v[14:15], 0, v[142:143]
	s_mov_b32 m0, s25
	s_ashr_i32 s28, s5, 8
	global_load_lds_dwordx4 v[14:15], off
	s_add_i32 m0, s11, 0x18000
	v_lshl_add_u64 v[4:5], v[4:5], 0, s[66:67]
	global_load_lds_dwordx4 v[4:5], off
	v_lshl_add_u64 v[4:5], v[6:7], 0, s[66:67]
	s_add_i32 m0, s11, 0x1a000
	s_add_i32 s30, s11, 0x8000
	global_load_lds_dwordx4 v[4:5], off
	v_lshl_add_u64 v[4:5], v[8:9], 0, s[66:67]
	s_mov_b32 m0, s30
	s_add_i32 s31, s11, 0xa000
	global_load_lds_dwordx4 v[4:5], off
	v_lshl_add_u64 v[4:5], v[10:11], 0, s[66:67]
	s_mov_b32 m0, s31
	s_nop 0
	global_load_lds_dwordx4 v[4:5], off
	v_lshl_add_u64 v[4:5], v[0:1], 0, s[84:85]
	s_add_i32 m0, s11, 0x1c000
	v_lshl_add_u64 v[6:7], v[4:5], 0, v[176:177]
	global_load_lds_dwordx4 v[6:7], off
	v_lshl_add_u64 v[4:5], v[4:5], 0, v[140:141]
	s_add_i32 m0, s11, 0x1e000
	s_nop 0
	global_load_lds_dwordx4 v[4:5], off
	s_cmp_eq_u32 s28, 1
	s_cselect_b64 s[14:15], -1, 0
	s_cmp_lg_u32 s28, 1
	s_cbranch_scc1 .LBB0_480
	s_barrier
.LBB0_480:
	s_add_u32 s16, s6, 0xa800000
	s_addc_u32 s17, s7, 0
	s_add_u32 s20, s6, 0x420000
	s_addc_u32 s21, s7, 0
	s_add_u32 s22, s6, 0x428000
	s_addc_u32 s23, s7, 0
	s_waitcnt vmcnt(2)
	s_barrier
	v_lshrrev_b32_e32 v14, 1, v12
	v_and_b32_e32 v14, 24, v14
	v_and_b32_e32 v13, 15, v12
	v_lshlrev_b32_e32 v15, 1, v14
	v_lshlrev_b32_e32 v12, 2, v12
	s_and_b32 s6, s4, 3
	v_lshl_or_b32 v150, s28, 6, v13
	v_lshl_or_b32 v13, v13, 6, v15
	s_lshl_b32 s7, s28, 13
	v_and_b32_e32 v12, 32, v12
	v_bitop3_b32 v15, v13, s7, v12 bitop3:0xde
	s_lshl_b32 s7, s4, 5
	s_lshl_b32 s6, s6, 12
	s_waitcnt vmcnt(6)
	s_cmpk_lt_u32 s5, 0x100
	v_readlane_b32 s42, v255, 40
	v_bitop3_b32 v151, v13, s6, v12 bitop3:0xde
	s_cselect_b64 s[40:41], -1, 0
	v_and_or_b32 v152, s7, 32, v14
	s_bfe_u32 s36, s4, 0x10001
	v_add_u32_e32 v153, 0, v15
	v_readlane_b32 s43, v255, 41
	v_readlane_b32 s4, v255, 35
	s_barrier
	s_branch .LBB0_483

; #define PG8_STAGE(bufoff, gbase, voff) do { _Pragma("unroll") for (int _i = 0; _i < 2; ++_i) \
;         __builtin_amdgcn_global_load_lds((const unsigned*)((const char*)(gbase) + (voff)[_i]), (PG8_LAS unsigned*)(lds + (bufoff) + ldsw + _i * 8192), 16, 0, 0); } while (0)
; #define PG8_LDA(dst, b, h) do { _Pragma("unroll") for (int m = 0; m < 4; ++m) _Pragma("unroll") for (int k = 0; k < 2; ++k) dst[m][k] = *(const PG8_LAS bf16x8*)(lds + PG8_SA(b, h) + aoff + m * 2048 + k * 1024); } while (0)
; #define PG8_LDB(dst, b, h) do { _Pragma("unroll") for (int n = 0; n < 2; ++n) _Pragma("unroll") for (int k = 0; k < 2; ++k) dst[n][k] = *(const PG8_LAS bf16x8*)(lds + PG8_SB(b, h) + boff + n * 2048 + k * 1024); } while (0)
; #define PG8_MMA(ai, bj, At, Bt) do { __builtin_amdgcn_s_setprio(1); _Pragma("unroll") for (int m = 0; m < 4; ++m) _Pragma("unroll") for (int n = 0; n < 2; ++n) _Pragma("unroll") for (int k = 0; k < 2; ++k) \
;         acc[ai][bj][m][n] = __builtin_amdgcn_mfma_f32_16x16x32_bf16(Bt[n][k], At[m][k], acc[ai][bj][m][n], 0, 0, 0); __builtin_amdgcn_s_setprio(0); } while (0)
; #define PG8_WAIT_V(n) asm volatile("s_waitcnt vmcnt(" #n ")" ::: "memory")
; #define PG8_WAIT_L(n) asm volatile("s_waitcnt lgkmcnt(" #n ")" ::: "memory")
; #define PG8_WAIT_VK do { if constexpr (HALFM) PG8_WAIT_V(6); else PG8_WAIT_V(8); } while (0)
; #define PG8_BAR __builtin_amdgcn_s_barrier()
; #define PG8_SCHED __builtin_amdgcn_sched_barrier(0)
; template <class Epi, class Sched, bool ALIGN_EPI = false, bool SP2 = false, bool HALFM = false, bool AMAP = false>
; __device__ __forceinline__ void gemm_phase(PG8_LAS unsigned char* lds, const Gemm g, const Sched& S, const Epi& E, int tid_in) {
;     ...
;         PG8_STAGE(PG8_SB(1, 0), cB + kstep, voffB); PG8_STAGE(PG8_SA(1, 0), cA + kstep, voffA); PG8_STAGE(PG8_SB(1, 1), cB + hstepB + kstep, voffB);
;         PG8_WAIT_V(6); PG8_BAR;
;     ...
;             PG8_LDB(B0, 0, 0); PG8_LDB(B1, 0, 1); PG8_SCHED; PG8_LDA(At, 0, 0); if constexpr (!HALFM) PG8_STAGE(PG8_SA(1, 1), a1 + hstepA, voffA);
;             PG8_WAIT_VK; PG8_WAIT_L(0); PG8_BAR; PG8_MMA(0, 0, At, B0); PG8_MMA(0, 1, At, B1); PG8_BAR; PG8_SCHED;
.LBB0_558:
	s_add_i32 s23, 0, 0x18000
	s_add_i32 s14, s23, s21
	v_lshl_add_u64 v[164:165], v[8:9], 0, s[66:67]
	s_mov_b32 m0, s14
	s_add_i32 s16, s14, 0x2000
	global_load_lds_dwordx4 v[164:165], off
	v_lshl_add_u64 v[166:167], v[10:11], 0, s[66:67]
	s_mov_b32 m0, s16
	s_add_i32 s15, s18, 0x8000
	global_load_lds_dwordx4 v[166:167], off
	v_lshl_add_u64 v[168:169], v[16:17], 0, s[66:67]
	s_mov_b32 m0, s15
	s_add_i32 s17, s18, 0xa000
	s_add_i32 s25, 0, 0x1c000
	global_load_lds_dwordx4 v[168:169], off
	v_lshl_add_u64 v[170:171], v[18:19], 0, s[66:67]
	s_mov_b32 m0, s17
	v_lshl_add_u64 v[24:25], v[24:25], 0, s[84:85]
	s_add_i32 s28, s25, s21
	global_load_lds_dwordx4 v[170:171], off
	v_lshl_add_u64 v[172:173], v[24:25], 0, v[176:177]
	s_mov_b32 m0, s28
	s_add_i32 s29, s28, 0x2000
	global_load_lds_dwordx4 v[172:173], off
	v_lshl_add_u64 v[174:175], v[24:25], 0, v[20:21]
	s_mov_b32 m0, s29
	s_nop 0
	global_load_lds_dwordx4 v[174:175], off
	s_waitcnt vmcnt(2)
	s_barrier
	v_and_b32_e32 v65, 15, v64
	v_and_b32_e32 v66, 48, v64
	v_lshlrev_b32_e32 v21, 2, v64
	s_and_b32 s13, s10, 3
	v_lshl_or_b32 v20, v65, 6, v66
	s_lshl_b32 s30, s5, 13
	v_and_b32_e32 v21, 32, v21
	v_bitop3_b32 v24, v20, s30, v21 bitop3:0xde
	s_lshl_b32 s30, s13, 12
	v_bitop3_b32 v20, v20, s30, v21 bitop3:0xde
	s_add_i32 s30, 0, 0x10000
	s_add_i32 s31, 0, 0x14000
	v_add_u32_e32 v32, s30, v20
	v_add_u32_e32 v48, s31, v20
	s_waitcnt vmcnt(6)
	s_barrier
	v_add_u32_e32 v67, 0, v24
	v_add_u32_e32 v120, s23, v20
	v_add_u32_e32 v128, s25, v20
	v_lshl_add_u64 v[88:89], v[22:23], 0, s[84:85]
	ds_read_b128 v[20:23], v32
	ds_read_b128 v[24:27], v32 offset:1024
	ds_read_b128 v[28:31], v32 offset:2048
	ds_read_b128 v[32:35], v32 offset:3072
	ds_read_b128 v[36:39], v48
	ds_read_b128 v[40:43], v48 offset:1024
	ds_read_b128 v[44:47], v48 offset:2048
	ds_read_b128 v[48:51], v48 offset:3072
	s_add_i32 s25, s30, s21
	s_add_i32 s21, s31, s21
	s_add_i32 m0, s18, 0xc000
	s_add_i32 s23, s18, 0xe000
	s_add_i32 s30, s25, 0x2000
	s_add_i32 s31, s21, 0x2000
	s_cmpk_gt_u32 s11, 0xff
	v_lshl_add_u64 v[0:1], v[88:89], 0, v[0:1]
	ds_read_b128 v[52:55], v67
	ds_read_b128 v[56:59], v67 offset:1024
	ds_read_b128 v[60:63], v67 offset:2048
	ds_read_b128 v[68:71], v67 offset:3072
	ds_read_b128 v[72:75], v67 offset:4096
	ds_read_b128 v[76:79], v67 offset:5120
	ds_read_b128 v[80:83], v67 offset:6144
	ds_read_b128 v[84:87], v67 offset:7168
	global_load_lds_dwordx4 v[0:1], off
	v_lshl_add_u64 v[0:1], v[88:89], 0, v[2:3]
	s_mov_b32 m0, s23
	s_nop 0
	global_load_lds_dwordx4 v[0:1], off
	s_waitcnt vmcnt(8)
	s_waitcnt lgkmcnt(0)
	s_barrier
	s_setprio 1
	s_waitcnt lgkmcnt(0)
	v_mfma_f32_16x16x32_bf16 v[0:3], v[20:23], v[52:55], 0
	v_mfma_f32_16x16x32_bf16 v[92:95], v[20:23], v[60:63], 0
	v_mfma_f32_16x16x32_bf16 v[100:103], v[20:23], v[72:75], 0
	v_mfma_f32_16x16x32_bf16 v[20:23], v[20:23], v[80:83], 0
	v_mfma_f32_16x16x32_bf16 v[0:3], v[24:27], v[56:59], v[0:3]
	v_mfma_f32_16x16x32_bf16 v[92:95], v[24:27], v[68:71], v[92:95]
	v_mfma_f32_16x16x32_bf16 v[100:103], v[24:27], v[76:79], v[100:103]
	v_mfma_f32_16x16x32_bf16 v[20:23], v[24:27], v[84:87], v[20:23]
	v_mfma_f32_16x16x32_bf16 v[24:27], v[28:31], v[80:83], 0
	v_mfma_f32_16x16x32_bf16 v[88:91], v[28:31], v[52:55], 0
	v_mfma_f32_16x16x32_bf16 v[96:99], v[28:31], v[60:63], 0
	v_mfma_f32_16x16x32_bf16 v[104:107], v[28:31], v[72:75], 0
	v_mfma_f32_16x16x32_bf16 v[28:31], v[32:35], v[84:87], v[24:27]
	v_mfma_f32_16x16x32_bf16 v[88:91], v[32:35], v[56:59], v[88:91]
	v_mfma_f32_16x16x32_bf16 v[96:99], v[32:35], v[68:71], v[96:99]
	v_mfma_f32_16x16x32_bf16 v[104:107], v[32:35], v[76:79], v[104:107]
	s_setprio 0
	s_setprio 1
	v_mfma_f32_16x16x32_bf16 v[24:27], v[36:39], v[52:55], 0
	v_mfma_f32_16x16x32_bf16 v[108:111], v[40:43], v[56:59], v[24:27]
	v_mfma_f32_16x16x32_bf16 v[24:27], v[44:47], v[52:55], 0
	v_mfma_f32_16x16x32_bf16 v[52:55], v[48:51], v[56:59], v[24:27]
	v_mfma_f32_16x16x32_bf16 v[24:27], v[36:39], v[60:63], 0
	v_mfma_f32_16x16x32_bf16 v[112:115], v[40:43], v[68:71], v[24:27]
	v_mfma_f32_16x16x32_bf16 v[24:27], v[44:47], v[60:63], 0
	v_mfma_f32_16x16x32_bf16 v[68:71], v[48:51], v[68:71], v[24:27]
	v_mfma_f32_16x16x32_bf16 v[24:27], v[36:39], v[72:75], 0
	v_mfma_f32_16x16x32_bf16 v[116:119], v[40:43], v[76:79], v[24:27]
	v_mfma_f32_16x16x32_bf16 v[24:27], v[44:47], v[72:75], 0
	v_mfma_f32_16x16x32_bf16 v[72:75], v[48:51], v[76:79], v[24:27]
	v_mfma_f32_16x16x32_bf16 v[24:27], v[36:39], v[80:83], 0
	v_mfma_f32_16x16x32_bf16 v[76:79], v[40:43], v[84:87], v[24:27]
	v_mfma_f32_16x16x32_bf16 v[24:27], v[44:47], v[80:83], 0
	v_mfma_f32_16x16x32_bf16 v[80:83], v[48:51], v[84:87], v[24:27]
	s_setprio 0
	s_barrier
; #define PG8_STAGE(bufoff, gbase, voff) do { _Pragma("unroll") for (int _i = 0; _i < 2; ++_i) \
;         __builtin_amdgcn_global_load_lds((const unsigned*)((const char*)(gbase) + (voff)[_i]), (PG8_LAS unsigned*)(lds + (bufoff) + ldsw + _i * 8192), 16, 0, 0); } while (0)
; #define PG8_LDA(dst, b, h) do { _Pragma("unroll") for (int m = 0; m < 4; ++m) _Pragma("unroll") for (int k = 0; k < 2; ++k) dst[m][k] = *(const PG8_LAS bf16x8*)(lds + PG8_SA(b, h) + aoff + m * 2048 + k * 1024); } while (0)
; #define PG8_LDB(dst, b, h) do { _Pragma("unroll") for (int n = 0; n < 2; ++n) _Pragma("unroll") for (int k = 0; k < 2; ++k) dst[n][k] = *(const PG8_LAS bf16x8*)(lds + PG8_SB(b, h) + boff + n * 2048 + k * 1024); } while (0)
; #define PG8_MMA(ai, bj, At, Bt) do { __builtin_amdgcn_s_setprio(1); _Pragma("unroll") for (int m = 0; m < 4; ++m) _Pragma("unroll") for (int n = 0; n < 2; ++n) _Pragma("unroll") for (int k = 0; k < 2; ++k) \
;         acc[ai][bj][m][n] = __builtin_amdgcn_mfma_f32_16x16x32_bf16(Bt[n][k], At[m][k], acc[ai][bj][m][n], 0, 0, 0); __builtin_amdgcn_s_setprio(0); } while (0)
; #define PG8_WAIT_L(n) asm volatile("s_waitcnt lgkmcnt(" #n ")" ::: "memory")
; #define PG8_BAR __builtin_amdgcn_s_barrier()
; template <class Epi, class Sched, bool ALIGN_EPI = false, bool SP2 = false, bool HALFM = false, bool AMAP = false>
; __device__ __forceinline__ void gemm_phase(PG8_LAS unsigned char* lds, const Gemm g, const Sched& S, const Epi& E, int tid_in) {
;     ...
;             if constexpr (!HALFM) { PG8_LDA(At, 0, 1); } PG8_STAGE(PG8_SB(0, 0), b2, voffB); PG8_STAGE(PG8_SB(0, 1), b2 + hstepB, voffB); PG8_STAGE(PG8_SA(0, 0), a2, voffA);
;             PG8_WAIT_VK; PG8_WAIT_L(0); PG8_BAR; if constexpr (!HALFM) { PG8_MMA(1, 0, At, B0); PG8_MMA(1, 1, At, B1); } PG8_BAR; PG8_SCHED;
;             PG8_LDB(B0, 1, 0); PG8_LDB(B1, 1, 1); PG8_SCHED; PG8_LDA(At, 1, 0); if constexpr (!HALFM) PG8_STAGE(PG8_SA(0, 1), a2 + hstepA, voffA);
;             PG8_WAIT_VK; PG8_WAIT_L(0); PG8_BAR; PG8_MMA(0, 0, At, B0); PG8_MMA(0, 1, At, B1); PG8_BAR; PG8_SCHED;
;             if constexpr (!HALFM) { PG8_LDA(At, 1, 1); } PG8_STAGE(PG8_SB(1, 0), b3, voffB); PG8_STAGE(PG8_SB(1, 1), b3 + hstepB, voffB); PG8_STAGE(PG8_SA(1, 0), a3, voffA);
;             PG8_WAIT_VK; PG8_WAIT_L(0); PG8_BAR; if constexpr (!HALFM) { PG8_MMA(1, 0, At, B0); PG8_MMA(1, 1, At, B1); } PG8_BAR; PG8_SCHED;
	s_mov_b32 m0, s25
	s_nop 0
	global_load_lds_dwordx4 v[8:9], off
	s_mov_b32 m0, s30
	s_nop 0
	global_load_lds_dwordx4 v[10:11], off
	s_mov_b32 m0, s21
	s_nop 0
	global_load_lds_dwordx4 v[12:13], off
	s_mov_b32 m0, s31
	s_nop 0
	global_load_lds_dwordx4 v[14:15], off
	s_mov_b32 m0, s18
	s_nop 0
	global_load_lds_dwordx4 v[16:17], off
	s_mov_b32 m0, s22
	s_nop 0
	global_load_lds_dwordx4 v[18:19], off
	s_waitcnt vmcnt(8)
	s_waitcnt lgkmcnt(0)
	s_barrier
	s_setprio 1
	s_setprio 0
	s_setprio 1
	s_setprio 0
	s_barrier
	ds_read_b128 v[8:11], v120
	ds_read_b128 v[12:15], v120 offset:1024
	ds_read_b128 v[36:39], v120 offset:2048
	ds_read_b128 v[44:47], v120 offset:3072
	ds_read_b128 v[84:87], v128
	ds_read_b128 v[120:123], v128 offset:1024
	ds_read_b128 v[124:127], v128 offset:2048
	ds_read_b128 v[128:131], v128 offset:3072
	s_mov_b32 m0, s19
	ds_read_b128 v[132:135], v67 offset:32768
	ds_read_b128 v[136:139], v67 offset:33792
	ds_read_b128 v[140:143], v67 offset:34816
	ds_read_b128 v[144:147], v67 offset:35840
	ds_read_b128 v[148:151], v67 offset:36864
	ds_read_b128 v[152:155], v67 offset:37888
	ds_read_b128 v[156:159], v67 offset:38912
	ds_read_b128 v[160:163], v67 offset:39936
	global_load_lds_dwordx4 v[4:5], off
	s_mov_b32 m0, s20
	s_nop 0
	global_load_lds_dwordx4 v[6:7], off
	s_waitcnt vmcnt(8)
	s_waitcnt lgkmcnt(0)
	s_barrier
	s_setprio 1
	s_waitcnt lgkmcnt(0)
	v_mfma_f32_16x16x32_bf16 v[0:3], v[8:11], v[132:135], v[0:3]
	v_mfma_f32_16x16x32_bf16 v[56:59], v[12:15], v[136:139], v[0:3]
	v_mfma_f32_16x16x32_bf16 v[0:3], v[36:39], v[132:135], v[88:91]
	v_mfma_f32_16x16x32_bf16 v[48:51], v[44:47], v[136:139], v[0:3]
	v_mfma_f32_16x16x32_bf16 v[0:3], v[8:11], v[140:143], v[92:95]
	v_mfma_f32_16x16x32_bf16 v[40:43], v[12:15], v[144:147], v[0:3]
	v_mfma_f32_16x16x32_bf16 v[0:3], v[36:39], v[140:143], v[96:99]
	v_mfma_f32_16x16x32_bf16 v[32:35], v[44:47], v[144:147], v[0:3]
	v_mfma_f32_16x16x32_bf16 v[0:3], v[8:11], v[148:151], v[100:103]
	v_mfma_f32_16x16x32_bf16 v[24:27], v[12:15], v[152:155], v[0:3]
	v_mfma_f32_16x16x32_bf16 v[0:3], v[36:39], v[148:151], v[104:107]
	v_mfma_f32_16x16x32_bf16 v[16:19], v[44:47], v[152:155], v[0:3]
	v_mfma_f32_16x16x32_bf16 v[0:3], v[8:11], v[156:159], v[20:23]
	v_mfma_f32_16x16x32_bf16 v[8:11], v[12:15], v[160:163], v[0:3]
	v_mfma_f32_16x16x32_bf16 v[0:3], v[36:39], v[156:159], v[28:31]
	v_mfma_f32_16x16x32_bf16 v[0:3], v[44:47], v[160:163], v[0:3]
	s_setprio 0
	s_setprio 1
	v_mfma_f32_16x16x32_bf16 v[4:7], v[84:87], v[132:135], v[108:111]
	v_mfma_f32_16x16x32_bf16 v[60:63], v[120:123], v[136:139], v[4:7]
	v_mfma_f32_16x16x32_bf16 v[4:7], v[124:127], v[132:135], v[52:55]
	v_mfma_f32_16x16x32_bf16 v[52:55], v[128:131], v[136:139], v[4:7]
	v_mfma_f32_16x16x32_bf16 v[4:7], v[84:87], v[140:143], v[112:115]
	v_mfma_f32_16x16x32_bf16 v[44:47], v[120:123], v[144:147], v[4:7]
	v_mfma_f32_16x16x32_bf16 v[4:7], v[124:127], v[140:143], v[68:71]
	v_mfma_f32_16x16x32_bf16 v[36:39], v[128:131], v[144:147], v[4:7]
	v_mfma_f32_16x16x32_bf16 v[4:7], v[84:87], v[148:151], v[116:119]
	v_mfma_f32_16x16x32_bf16 v[28:31], v[120:123], v[152:155], v[4:7]
	v_mfma_f32_16x16x32_bf16 v[4:7], v[124:127], v[148:151], v[72:75]
	v_mfma_f32_16x16x32_bf16 v[20:23], v[128:131], v[152:155], v[4:7]
	v_mfma_f32_16x16x32_bf16 v[4:7], v[84:87], v[156:159], v[76:79]
	v_mfma_f32_16x16x32_bf16 v[12:15], v[120:123], v[160:163], v[4:7]
	v_mfma_f32_16x16x32_bf16 v[4:7], v[124:127], v[156:159], v[80:83]
	v_mfma_f32_16x16x32_bf16 v[4:7], v[128:131], v[160:163], v[4:7]
	s_setprio 0
	s_barrier
	s_mov_b32 m0, s14
	s_nop 0
	global_load_lds_dwordx4 v[164:165], off
	s_mov_b32 m0, s16
	s_nop 0
	global_load_lds_dwordx4 v[166:167], off
	s_mov_b32 m0, s28
	s_nop 0
	global_load_lds_dwordx4 v[172:173], off
	s_mov_b32 m0, s29
	s_nop 0
	global_load_lds_dwordx4 v[174:175], off
	s_mov_b32 m0, s15
	s_nop 0
	global_load_lds_dwordx4 v[168:169], off
	s_mov_b32 m0, s17
	s_nop 0
	global_load_lds_dwordx4 v[170:171], off
	s_waitcnt vmcnt(8)
	s_waitcnt lgkmcnt(0)
	s_barrier
	s_setprio 1
	s_setprio 0
	s_setprio 1
	s_setprio 0
	s_barrier
	s_cbranch_scc1 .LBB0_549
	s_barrier
	s_branch .LBB0_549

; #define PG8_LAS __attribute__((address_space(3)))
; #define PG8_STAGE(bufoff, gbase, voff) do { _Pragma("unroll") for (int _i = 0; _i < 2; ++_i) \
;         __builtin_amdgcn_global_load_lds((const unsigned*)((const char*)(gbase) + (voff)[_i]), (PG8_LAS unsigned*)(lds + (bufoff) + ldsw + _i * 8192), 16, 0, 0); } while (0)
; #define PG8_WAIT_V(n) asm volatile("s_waitcnt vmcnt(" #n ")" ::: "memory")
; #define PG8_BAR __builtin_amdgcn_s_barrier()
; template <class Epi, class Sched, bool ALIGN_EPI = false, bool SP2 = false, bool HALFM = false, bool AMAP = false>
; __device__ __forceinline__ void gemm_phase(PG8_LAS unsigned char* lds, const Gemm g, const Sched& S, const Epi& E, int tid_in) {
;     ...
;     for (int i = 0; i < 2; ++i) { int R, C; stage_rc(tid * 16 + i * 8192, R, C); const int Rb = Epi::PERM ? ((R & ~31) + perm32(R & 31)) : R;
;         const int Ra = AMAP ? (64 * ((R >> 4) & 3) + 16 * (R >> 6) + (R & 15)) : R;
;         voffA[i] = (unsigned)(Ra * g.lda + C) * 2u; voffB[i] = (unsigned)(Rb * g.ldb + C) * 2u; }
;     ...
;     const char* cA = gA + PG8_ATILE(cur.pm); const char* cB = gB + (size_t)cur.pn * tstepB;
;     S.a_ready(cur);
;     if constexpr (SP2) {
;         PG8_STAGE(PG8_SB(0, 0), cB, voffB); PG8_STAGE(PG8_SB(0, 1), cB + hstepB, voffB); PG8_STAGE(PG8_SA(0, 0), cA, voffA); if constexpr (!HALFM) PG8_STAGE(PG8_SA(0, 1), cA + hstepA, voffA);
;         if constexpr (Epi::RSTD) E.prime((PG8_LAS float*)(lds + STAGE_BYTES), cur, tid);
;         if (wr == 1) PG8_BAR;
;         if constexpr (HALFM) PG8_WAIT_V(0); else PG8_WAIT_V(2);
;         PG8_BAR;
;         PG8_STAGE(PG8_SB(1, 0), cB + kstep, voffB); PG8_STAGE(PG8_SA(1, 0), cA + kstep, voffA); PG8_STAGE(PG8_SB(1, 1), cB + hstepB + kstep, voffB);
.LBB0_637:
	s_or_b64 exec, exec, s[6:7]
	s_mov_b64 s[4:5], s[0:1]
	s_waitcnt lgkmcnt(0)
	s_barrier
	s_load_dwordx2 s[6:7], s[4:5], 0xa8
	v_readlane_b32 s4, v255, 53
	v_readlane_b32 s5, v255, 54
	v_mbcnt_lo_u32_b32 v0, -1, 0
	v_mbcnt_hi_u32_b32 v0, -1, v0
	s_waitcnt lgkmcnt(0)
	s_add_u32 s8, s6, 0xc800000
	s_addc_u32 s9, s7, 0
	s_add_u32 s4, s6, s4
	s_addc_u32 s5, s7, s5
	s_add_u32 s12, s4, 0x39800000
	s_addc_u32 s13, s5, 0
	v_or_b32_e32 v14, s92, v0
	s_and_b64 vcc, exec, s[90:91]
	v_readfirstlane_b32 s4, v14
	s_cbranch_vccnz .LBB0_673
	v_lshlrev_b32_e32 v0, 4, v14
	v_add_u32_e32 v1, 0x2000, v0
	v_ashrrev_i32_e32 v2, 31, v1
	v_lshrrev_b32_e32 v2, 22, v2
	v_add_u32_e32 v2, v1, v2
	v_ashrrev_i32_e32 v8, 10, v2
	v_mul_i32_i24_e32 v2, 0x400, v8
	v_sub_u32_e32 v1, v1, v2
	v_lshrrev_b32_e32 v2, 4, v1
	v_bitop3_b32 v1, v2, v1, 32 bitop3:0x6c
	v_ashrrev_i32_e32 v2, 31, v1
	v_lshrrev_b32_e32 v2, 26, v2
	v_add_u32_e32 v2, v1, v2
	v_lshlrev_b32_e32 v3, 3, v8
	v_ashrrev_i32_e32 v9, 6, v2
	v_and_b32_e32 v3, -16, v3
	v_add_u32_e32 v3, v9, v3
	v_and_b32_e32 v4, 3, v9
	s_mov_b32 s11, 0xfffe0
	v_lshrrev_b32_e32 v5, 2, v3
	v_lshlrev_b32_e32 v6, 1, v3
	v_and_b32_e32 v2, 0xc0, v2
	v_and_or_b32 v4, v3, s11, v4
	v_and_b32_e32 v5, 4, v5
	v_and_b32_e32 v6, 24, v6
	v_sub_u32_e32 v1, v1, v2
	v_or3_b32 v4, v4, v5, v6
	v_lshlrev_b32_e32 v5, 5, v8
	v_ashrrev_i16_sdwa v1, v254, sext(v1) dst_sel:DWORD dst_unused:UNUSED_PAD src0_sel:DWORD src1_sel:BYTE_0
	v_and_b32_e32 v5, 32, v5
	v_bfe_i32 v10, v1, 0, 16
	v_add_lshl_u32 v1, v5, v10, 1
	v_lshl_add_u32 v152, v4, 12, v1
	v_lshl_add_u32 v154, v3, 12, v1
	v_bfe_i32 v1, v14, 27, 1
	v_lshrrev_b32_e32 v1, 22, v1
	v_add_u32_e32 v1, v0, v1
	v_and_b32_e32 v1, 0xfffffc00, v1
	v_sub_u32_e32 v0, v0, v1
	v_lshrrev_b32_e32 v1, 4, v0
	v_ashrrev_i32_e32 v2, 31, v14
	v_bitop3_b32 v0, v1, v0, 32 bitop3:0x6c
	v_lshrrev_b32_e32 v2, 26, v2
	v_ashrrev_i32_e32 v1, 31, v0
	v_add_u32_e32 v2, v14, v2
	v_lshrrev_b32_e32 v1, 26, v1
	v_ashrrev_i32_e32 v12, 6, v2
	v_add_u32_e32 v1, v0, v1
	v_lshlrev_b32_e32 v2, 3, v12
	v_ashrrev_i32_e32 v11, 6, v1
	v_and_b32_e32 v2, -16, v2
	v_add_u32_e32 v2, v11, v2
	v_and_b32_e32 v3, 3, v11
	v_lshrrev_b32_e32 v4, 2, v2
	v_lshlrev_b32_e32 v5, 1, v2
	v_and_b32_e32 v1, 0xc0, v1
	v_and_or_b32 v3, v2, s11, v3
	v_and_b32_e32 v4, 4, v4
	v_and_b32_e32 v5, 24, v5
	v_sub_u32_e32 v0, v0, v1
	v_or3_b32 v3, v3, v4, v5
	v_lshlrev_b32_e32 v4, 5, v12
	v_ashrrev_i16_sdwa v0, v254, sext(v0) dst_sel:DWORD dst_unused:UNUSED_PAD src0_sel:DWORD src1_sel:BYTE_0
	v_and_b32_e32 v4, 32, v4
	v_bfe_i32 v13, v0, 0, 16
	v_readlane_b32 s14, v255, 29
	s_ashr_i32 s22, s4, 6
	v_add_lshl_u32 v0, v4, v13, 1
	v_readlane_b32 s15, v255, 30
	s_lshl_b32 s10, s22, 10
	v_lshl_add_u32 v176, v3, 12, v0
	v_lshl_add_u32 v156, v2, 12, v0
	v_mov_b64_e32 v[0:1], s[14:15]
	v_lshl_add_u64 v[4:5], s[12:13], 0, v[0:1]
	s_add_i32 s11, s10, 0
	s_add_i32 m0, s11, 0x10000
	v_lshl_add_u64 v[0:1], v[4:5], 0, v[176:177]
	v_mov_b32_e32 v153, v177
	s_mov_b64 s[16:17], 0x80000
	v_readfirstlane_b32 s28, v4
	v_readfirstlane_b32 s29, v5
	global_load_lds_dwordx4 v[0:1], off
	v_lshl_add_u64 v[2:3], v[4:5], 0, v[152:153]
	s_add_i32 m0, s11, 0x12000
	v_lshl_add_u64 v[4:5], v[4:5], 0, s[16:17]
	global_load_lds_dwordx4 v[2:3], off
	s_add_i32 m0, s11, 0x14000
	v_lshl_add_u64 v[6:7], v[4:5], 0, v[176:177]
	v_readlane_b32 s14, v255, 27
	global_load_lds_dwordx4 v[6:7], off
	v_lshl_add_u64 v[4:5], v[4:5], 0, v[152:153]
	s_add_i32 m0, s11, 0x16000
	v_readlane_b32 s15, v255, 28
	global_load_lds_dwordx4 v[4:5], off
	s_nop 0
	v_mov_b64_e32 v[4:5], s[14:15]
	v_lshl_add_u64 v[16:17], s[8:9], 0, v[4:5]
	v_mov_b32_e32 v157, v177
	v_lshl_add_u64 v[4:5], v[16:17], 0, v[156:157]
	s_mov_b32 m0, s11
	v_mov_b32_e32 v155, v177
	s_add_i32 s18, s11, 0x2000
	v_readfirstlane_b32 s30, v16
	v_readfirstlane_b32 s31, v17
	global_load_lds_dwordx4 v[4:5], off
	v_lshl_add_u64 v[6:7], v[16:17], 0, v[154:155]
	s_mov_b32 m0, s18
	v_lshl_add_u64 v[16:17], v[16:17], 0, s[16:17]
	s_add_i32 s19, s11, 0x4000
	global_load_lds_dwordx4 v[6:7], off
	v_lshl_add_u64 v[18:19], v[16:17], 0, v[156:157]
	s_mov_b32 m0, s19
	s_add_i32 s25, s11, 0x6000
	global_load_lds_dwordx4 v[18:19], off
	v_lshl_add_u64 v[16:17], v[16:17], 0, v[154:155]
	s_mov_b32 m0, s25
	s_ashr_i32 s5, s4, 8
	global_load_lds_dwordx4 v[16:17], off
	s_add_i32 m0, s11, 0x18000
	v_lshl_add_u64 v[0:1], v[0:1], 0, s[66:67]
	global_load_lds_dwordx4 v[0:1], off
	v_lshl_add_u64 v[0:1], v[2:3], 0, s[66:67]
	s_add_i32 m0, s11, 0x1a000
	s_add_i32 s39, s11, 0x8000
	s_add_i32 s58, s11, 0xa000
	global_load_lds_dwordx4 v[0:1], off
	v_lshl_add_u64 v[0:1], v[4:5], 0, s[66:67]
	s_mov_b32 m0, s39
	s_add_u32 s100, s28, 0x80080
	global_load_lds_dwordx4 v[0:1], off
	v_lshl_add_u64 v[0:1], v[6:7], 0, s[66:67]
	s_mov_b32 m0, s58
	s_addc_u32 s101, s29, 0
	global_load_lds_dwordx4 v[0:1], off
	s_add_i32 m0, s11, 0x1c000
	v_lshl_add_u64 v[0:1], s[100:101], 0, v[176:177]
	global_load_lds_dwordx4 v[0:1], off
	v_lshl_add_u64 v[0:1], s[100:101], 0, v[152:153]
	s_add_i32 m0, s11, 0x1e000
	s_nop 0
	global_load_lds_dwordx4 v[0:1], off
	s_cmp_eq_u32 s5, 1
	s_cselect_b64 s[14:15], -1, 0
	s_cmp_lg_u32 s5, 1
	s_cbranch_scc1 .LBB0_640
	s_barrier
.LBB0_640:
	s_add_u32 s16, s6, 0x1000000
	s_addc_u32 s17, s7, 0
	v_bfe_u32 v15, v14, 4, 2
	s_add_u32 s20, s6, 0x300000
	v_and_b32_e32 v16, 15, v14
	v_lshlrev_b32_e32 v17, 4, v15
	v_lshlrev_b32_e32 v14, 2, v14
	s_addc_u32 s21, s7, 0
	s_and_b32 s38, s22, 3
	v_lshl_or_b32 v188, s5, 6, v16
	v_lshl_or_b32 v16, v16, 6, v17
	s_lshl_b32 s5, s5, 13
	v_and_b32_e32 v14, 32, v14
	v_bitop3_b32 v17, v16, s5, v14 bitop3:0xde
	s_lshl_b32 s5, s38, 5
	s_lshl_b32 s6, s38, 12
	s_waitcnt vmcnt(2)
	s_barrier
	v_bitop3_b32 v189, v16, s6, v14 bitop3:0xde
	s_mov_b32 s6, s100
	s_mov_b32 s7, s101
	s_cmpk_lt_u32 s4, 0x100
	v_lshlrev_b32_e32 v0, 15, v8
	v_and_b32_e32 v0, 0xffff0000, v0
	v_lshl_add_u32 v0, v9, 12, v0
	v_and_b32_e32 v1, 1, v8
	v_lshl_or_b32 v0, v1, 6, v0
	v_lshl_add_u32 v158, v10, 1, v0
	v_lshlrev_b32_e32 v0, 15, v12
	v_and_b32_e32 v0, 0xffff0000, v0
	s_waitcnt vmcnt(6)
	v_lshl_add_u32 v0, v11, 12, v0
	v_and_b32_e32 v1, 1, v12
	v_lshl_or_b32 v0, v1, 6, v0
	v_readlane_b32 s6, v255, 25
	s_cselect_b64 s[22:23], -1, 0
	v_lshl_or_b32 v190, v15, 3, s5
	s_mov_b32 s59, 0
	v_cmp_eq_u32_e64 s[4:5], 0, v15
	v_mov_b32_e32 v159, v177
	v_lshl_add_u32 v160, v13, 1, v0
	v_mov_b32_e32 v161, v177
	v_add_u32_e32 v191, 0, v17
	v_readlane_b32 s60, v255, 13
	s_mov_b32 s61, s6
	s_barrier
	v_readlane_b32 s7, v255, 26
	s_branch .LBB0_643

; #define LAS __attribute__((address_space(3)))
; __global__ void __launch_bounds__(NWAVES * 64, 2) enc_fwd(Args args_unused) {
;     extern __shared__ __attribute__((aligned(16))) unsigned char lds_raw[];
;     LAS unsigned char* lds = (LAS unsigned char*)lds_raw;
;     const int wave_s = __builtin_amdgcn_readfirstlane((int)threadIdx.x >> 6);
	.amdhsa_kernel _Z7enc_fwd4Args
		.amdhsa_group_segment_fixed_size 0
		.amdhsa_private_segment_fixed_size 0
		.amdhsa_kernarg_size 448
		.amdhsa_user_sgpr_count 2
		.amdhsa_user_sgpr_dispatch_ptr 0
		.amdhsa_user_sgpr_queue_ptr 0
		.amdhsa_user_sgpr_kernarg_segment_ptr 1
		.amdhsa_user_sgpr_dispatch_id 0
		.amdhsa_user_sgpr_kernarg_preload_length 0
		.amdhsa_user_sgpr_kernarg_preload_offset 0
		.amdhsa_user_sgpr_private_segment_size 0
		.amdhsa_uses_dynamic_stack 0
		.amdhsa_enable_private_segment 0
		.amdhsa_system_sgpr_workgroup_id_x 1
		.amdhsa_system_sgpr_workgroup_id_y 0
		.amdhsa_system_sgpr_workgroup_id_z 0
		.amdhsa_system_sgpr_workgroup_info 0
		.amdhsa_system_vgpr_workitem_id 0
		.amdhsa_next_free_vgpr 256
		.amdhsa_next_free_sgpr 102
		.amdhsa_accum_offset 256
		.amdhsa_reserve_vcc 1
		.amdhsa_float_round_mode_32 0
		.amdhsa_float_round_mode_16_64 0
		.amdhsa_float_denorm_mode_32 3
		.amdhsa_float_denorm_mode_16_64 3
		.amdhsa_dx10_clamp 1
		.amdhsa_ieee_mode 1
		.amdhsa_fp16_overflow 0
		.amdhsa_tg_split 0
		.amdhsa_exception_fp_ieee_invalid_op 0
		.amdhsa_exception_fp_denorm_src 0
		.amdhsa_exception_fp_ieee_div_zero 0
		.amdhsa_exception_fp_ieee_overflow 0
		.amdhsa_exception_fp_ieee_underflow 0
		.amdhsa_exception_fp_ieee_inexact 0
		.amdhsa_exception_int_div_zero 0
	.end_amdhsa_kernel

; #define LAS __attribute__((address_space(3)))
; __global__ void __launch_bounds__(NWAVES * 64, 2) enc_fwd(Args args_unused) {
;     extern __shared__ __attribute__((aligned(16))) unsigned char lds_raw[];
;     LAS unsigned char* lds = (LAS unsigned char*)lds_raw;
;     const int wave_s = __builtin_amdgcn_readfirstlane((int)threadIdx.x >> 6);
amdhsa.kernels:
  - .agpr_count:     0
    .args:
      - .offset:         0
        .size:           192
        .value_kind:     by_value
      - .offset:         192
        .size:           4
        .value_kind:     hidden_block_count_x
      - .offset:         196
        .size:           4
        .value_kind:     hidden_block_count_y
      - .offset:         200
        .size:           4
        .value_kind:     hidden_block_count_z
      - .offset:         204
        .size:           2
        .value_kind:     hidden_group_size_x
      - .offset:         206
        .size:           2
        .value_kind:     hidden_group_size_y
      - .offset:         208
        .size:           2
        .value_kind:     hidden_group_size_z
      - .offset:         210
        .size:           2
        .value_kind:     hidden_remainder_x
      - .offset:         212
        .size:           2
        .value_kind:     hidden_remainder_y
      - .offset:         214
        .size:           2
        .value_kind:     hidden_remainder_z
      - .offset:         232
        .size:           8
        .value_kind:     hidden_global_offset_x
      - .offset:         240
        .size:           8
        .value_kind:     hidden_global_offset_y
      - .offset:         248
        .size:           8
        .value_kind:     hidden_global_offset_z
      - .offset:         256
        .size:           2
        .value_kind:     hidden_grid_dims
      - .offset:         312
        .size:           4
        .value_kind:     hidden_dynamic_lds_size
    .group_segment_fixed_size: 0
    .kernarg_segment_align: 8
    .kernarg_segment_size: 448
    .language:       OpenCL C
    .language_version:
      - 2
      - 0
    .max_flat_workgroup_size: 512
    .name:           _Z7enc_fwd4Args
    .private_segment_fixed_size: 0
    .sgpr_count:     108
    .sgpr_spill_count: 66
    .symbol:         _Z7enc_fwd4Args.kd
    .uniform_work_group_size: 1
    .uses_dynamic_stack: false
    .vgpr_count:     256
    .vgpr_spill_count: 0
    .wavefront_size: 64
